# grid barrier 3 replaced by a producer counter (136 P2b GEMM workgroups publish with write-through stores + one atomic; every workgroup polls it before attention); conv workgroups no longer gate it
# speedup vs baseline: 1.0307x; 1.0046x over previous
; __device__ __forceinline__ unsigned cvtpk(float lo, float hi) { f32x2 v = {lo, hi}; bf16x2_t b = __builtin_convertvector(v, bf16x2_t); return __builtin_bit_cast(unsigned, b); }
; __device__ __forceinline__ float sigmoid_f(float v) { return __builtin_amdgcn_rcpf(1.0f + __builtin_amdgcn_exp2f(-v * LOG2E)); }
;     __device__ __forceinline__ void operator()(const f32x4 (&acc)[2][2][4][2], const pg8::Unit& u, int wr, int wc, int fr, int fq) const {
;     ...
;         } else if (kind == 2) {
;             const int pnl = u.pn - 12;
;             bf16_t* Y = (bf16_t*)(ws + WS_Y);
; #pragma unroll
;             for (int ai = 0; ai < 2; ++ai)
; #pragma unroll
;                 for (int m = 0; m < 4; ++m) {
;                     const int t = 256 * u.pm + 128 * ai + 64 * wr + 16 * m + fr;
;                     bf16_t* rowp = Y + (size_t)t * 1024 + 128 * pnl + 32 * wc + 8 * fq;
;                     const f32x4 a0 = acc[ai][0][m][0], a1 = acc[ai][0][m][1], g0 = acc[ai][1][m][0], g1 = acc[ai][1][m][1];
;                     u32x4 w; w.x = cvtpk(a0[0] * sigmoid_f(g0[0]), a0[1] * sigmoid_f(g0[1])); w.y = cvtpk(a0[2] * sigmoid_f(g0[2]), a0[3] * sigmoid_f(g0[3]));
;                     w.z = cvtpk(a1[0] * sigmoid_f(g1[0]), a1[1] * sigmoid_f(g1[1])); w.w = cvtpk(a1[2] * sigmoid_f(g1[2]), a1[3] * sigmoid_f(g1[3]));
;                     *(u32x4*)rowp = w;
;                 }
.LBB0_600:
	s_cmp_eq_u32 s46, 2
	s_mov_b64 s[20:21], -1
	s_cbranch_scc0 .LBB0_602
	s_lshl_b32 s8, s68, 7
	v_mul_f32_e32 v130, 0xbfb8aa3b, v116
	s_add_i32 s20, s8, 0xfffffa00
	v_exp_f32_e32 v131, v130
	v_mul_f32_e32 v130, 0xbfb8aa3b, v117
	s_ashr_i32 s21, s20, 31
	v_exp_f32_e32 v133, v130
	s_lshl_b64 s[20:21], s[20:21], 1
	s_add_u32 s8, s44, s20
	s_addc_u32 s21, s45, s21
	s_lshl_b32 s20, s53, 1
	v_add_f32_e32 v131, 1.0, v131
	s_add_u32 s20, s8, s20
	v_rcp_f32_e32 v132, v131
	v_add_f32_e32 v131, 1.0, v133
	s_addc_u32 s21, s21, 0
	s_lshl_b32 s8, s67, 8
	v_rcp_f32_e32 v133, v131
	v_lshlrev_b32_e32 v166, 1, v164
	v_add_u32_e32 v130, s8, v169
	v_lshl_add_u64 v[128:129], s[20:21], 0, v[166:167]
	v_ashrrev_i32_e32 v131, 31, v130
	v_lshl_add_u64 v[128:129], v[128:129], 0, s[18:19]
	v_lshlrev_b64 v[130:131], 11, v[130:131]
	v_lshl_add_u64 v[134:135], v[128:129], 0, v[130:131]
	v_pk_mul_f32 v[130:131], v[124:125], v[132:133]
	v_mul_f32_e32 v132, 0xbfb8aa3b, v118
	v_exp_f32_e32 v132, v132
	v_mul_f32_e32 v133, 0xbfb8aa3b, v119
	v_exp_f32_e32 v133, v133
	v_cvt_pk_bf16_f32 v130, v130, v131
	v_add_f32_e32 v131, 1.0, v132
	v_rcp_f32_e32 v132, v131
	v_add_f32_e32 v131, 1.0, v133
	v_rcp_f32_e32 v133, v131
	v_mul_f32_e32 v131, 0xbfb8aa3b, v112
	v_exp_f32_e32 v131, v131
	v_mul_f32_e32 v136, 0xbfb8aa3b, v113
	v_exp_f32_e32 v137, v136
	v_pk_mul_f32 v[132:133], v[126:127], v[132:133]
	v_add_f32_e32 v131, 1.0, v131
	v_rcp_f32_e32 v136, v131
	v_add_f32_e32 v131, 1.0, v137
	v_mul_f32_e32 v137, 0xbfb8aa3b, v114
	v_exp_f32_e32 v138, v137
	v_mul_f32_e32 v137, 0xbfb8aa3b, v115
	v_exp_f32_e32 v139, v137
	v_rcp_f32_e32 v137, v131
	v_add_f32_e32 v131, 1.0, v138
	v_rcp_f32_e32 v138, v131
	v_add_f32_e32 v131, 1.0, v139
	v_rcp_f32_e32 v139, v131
	v_cvt_pk_bf16_f32 v131, v132, v133
	v_pk_mul_f32 v[132:133], v[120:121], v[136:137]
	s_mov_b64 s[20:21], 0
	v_pk_mul_f32 v[136:137], v[122:123], v[138:139]
	v_cvt_pk_bf16_f32 v132, v132, v133
	v_cvt_pk_bf16_f32 v133, v136, v137
	global_store_dwordx4 v[134:135], v[130:133], off sc1
	v_mul_f32_e32 v136, 0xbfb8aa3b, v97
	v_exp_f32_e32 v137, v136
	v_mul_f32_e32 v130, 0xbfb8aa3b, v100
	v_exp_f32_e32 v131, v130
	v_mul_f32_e32 v130, 0xbfb8aa3b, v101
	v_exp_f32_e32 v133, v130
	v_add_u32_e32 v130, s8, v190
	v_add_f32_e32 v131, 1.0, v131
	v_rcp_f32_e32 v132, v131
	v_add_f32_e32 v131, 1.0, v133
	v_rcp_f32_e32 v133, v131
	v_ashrrev_i32_e32 v131, 31, v130
	v_lshlrev_b64 v[130:131], 11, v[130:131]
	v_lshl_add_u64 v[134:135], v[128:129], 0, v[130:131]
	v_pk_mul_f32 v[130:131], v[108:109], v[132:133]
	v_mul_f32_e32 v132, 0xbfb8aa3b, v102
	v_exp_f32_e32 v132, v132
	v_mul_f32_e32 v133, 0xbfb8aa3b, v103
	v_exp_f32_e32 v133, v133
	v_cvt_pk_bf16_f32 v130, v130, v131
	v_add_f32_e32 v131, 1.0, v132
	v_rcp_f32_e32 v132, v131
	v_add_f32_e32 v131, 1.0, v133
	v_rcp_f32_e32 v133, v131
	v_mul_f32_e32 v131, 0xbfb8aa3b, v96
	v_exp_f32_e32 v131, v131
	s_mov_b64 s[28:29], 0
	v_pk_mul_f32 v[132:133], v[110:111], v[132:133]
	v_add_f32_e32 v131, 1.0, v131
	v_rcp_f32_e32 v136, v131
	v_add_f32_e32 v131, 1.0, v137
	v_mul_f32_e32 v137, 0xbfb8aa3b, v98
	v_exp_f32_e32 v138, v137
	v_mul_f32_e32 v137, 0xbfb8aa3b, v99
	v_exp_f32_e32 v139, v137
	v_rcp_f32_e32 v137, v131
	v_add_f32_e32 v131, 1.0, v138
	v_rcp_f32_e32 v138, v131
	v_add_f32_e32 v131, 1.0, v139
	v_rcp_f32_e32 v139, v131
	v_cvt_pk_bf16_f32 v131, v132, v133
	v_pk_mul_f32 v[132:133], v[104:105], v[136:137]
	v_pk_mul_f32 v[136:137], v[106:107], v[138:139]
	v_cvt_pk_bf16_f32 v132, v132, v133
	v_cvt_pk_bf16_f32 v133, v136, v137
	global_store_dwordx4 v[134:135], v[130:133], off sc1
	v_mul_f32_e32 v136, 0xbfb8aa3b, v81
	v_exp_f32_e32 v137, v136
	v_mul_f32_e32 v130, 0xbfb8aa3b, v84
	v_exp_f32_e32 v131, v130
	v_mul_f32_e32 v130, 0xbfb8aa3b, v85
	v_exp_f32_e32 v133, v130
	v_add_u32_e32 v130, s8, v191
	v_add_f32_e32 v131, 1.0, v131
	v_rcp_f32_e32 v132, v131
	v_add_f32_e32 v131, 1.0, v133
	v_rcp_f32_e32 v133, v131
	v_ashrrev_i32_e32 v131, 31, v130
	v_lshlrev_b64 v[130:131], 11, v[130:131]
	v_lshl_add_u64 v[134:135], v[128:129], 0, v[130:131]
	v_pk_mul_f32 v[130:131], v[92:93], v[132:133]
	v_mul_f32_e32 v132, 0xbfb8aa3b, v86
	v_exp_f32_e32 v132, v132
	v_mul_f32_e32 v133, 0xbfb8aa3b, v87
	v_exp_f32_e32 v133, v133
	v_cvt_pk_bf16_f32 v130, v130, v131
	v_add_f32_e32 v131, 1.0, v132
	v_rcp_f32_e32 v132, v131
	v_add_f32_e32 v131, 1.0, v133
	v_rcp_f32_e32 v133, v131
	v_mul_f32_e32 v131, 0xbfb8aa3b, v80
	v_exp_f32_e32 v131, v131
	v_pk_mul_f32 v[132:133], v[94:95], v[132:133]
	v_add_f32_e32 v131, 1.0, v131
	v_rcp_f32_e32 v136, v131
	v_add_f32_e32 v131, 1.0, v137
	v_mul_f32_e32 v137, 0xbfb8aa3b, v82
	v_exp_f32_e32 v138, v137
	v_mul_f32_e32 v137, 0xbfb8aa3b, v83
	v_exp_f32_e32 v139, v137
	v_rcp_f32_e32 v137, v131
	v_add_f32_e32 v131, 1.0, v138
	v_rcp_f32_e32 v138, v131
	v_add_f32_e32 v131, 1.0, v139
	v_rcp_f32_e32 v139, v131
	v_cvt_pk_bf16_f32 v131, v132, v133
	v_pk_mul_f32 v[132:133], v[88:89], v[136:137]
	v_pk_mul_f32 v[136:137], v[90:91], v[138:139]
	v_cvt_pk_bf16_f32 v132, v132, v133
	v_cvt_pk_bf16_f32 v133, v136, v137
	global_store_dwordx4 v[134:135], v[130:133], off sc1
	v_mul_f32_e32 v136, 0xbfb8aa3b, v65
	v_exp_f32_e32 v137, v136
	v_mul_f32_e32 v130, 0xbfb8aa3b, v68
	v_exp_f32_e32 v131, v130
	v_mul_f32_e32 v130, 0xbfb8aa3b, v69
	v_exp_f32_e32 v133, v130
	v_add_u32_e32 v130, s8, v192
	v_add_f32_e32 v131, 1.0, v131
	v_rcp_f32_e32 v132, v131
	v_add_f32_e32 v131, 1.0, v133
	v_rcp_f32_e32 v133, v131
	v_ashrrev_i32_e32 v131, 31, v130
	v_lshlrev_b64 v[130:131], 11, v[130:131]
	v_lshl_add_u64 v[134:135], v[128:129], 0, v[130:131]
	v_pk_mul_f32 v[130:131], v[76:77], v[132:133]
	v_mul_f32_e32 v132, 0xbfb8aa3b, v70
	v_exp_f32_e32 v132, v132
; __device__ __forceinline__ unsigned cvtpk(float lo, float hi) { f32x2 v = {lo, hi}; bf16x2_t b = __builtin_convertvector(v, bf16x2_t); return __builtin_bit_cast(unsigned, b); }
; __device__ __forceinline__ float sigmoid_f(float v) { return __builtin_amdgcn_rcpf(1.0f + __builtin_amdgcn_exp2f(-v * LOG2E)); }
;     __device__ __forceinline__ void operator()(const f32x4 (&acc)[2][2][4][2], const pg8::Unit& u, int wr, int wc, int fr, int fq) const {
;     ...
;         } else if (kind == 2) {
;             const int pnl = u.pn - 12;
;             bf16_t* Y = (bf16_t*)(ws + WS_Y);
; #pragma unroll
;             for (int ai = 0; ai < 2; ++ai)
; #pragma unroll
;                 for (int m = 0; m < 4; ++m) {
;                     const int t = 256 * u.pm + 128 * ai + 64 * wr + 16 * m + fr;
;                     bf16_t* rowp = Y + (size_t)t * 1024 + 128 * pnl + 32 * wc + 8 * fq;
;                     const f32x4 a0 = acc[ai][0][m][0], a1 = acc[ai][0][m][1], g0 = acc[ai][1][m][0], g1 = acc[ai][1][m][1];
;                     u32x4 w; w.x = cvtpk(a0[0] * sigmoid_f(g0[0]), a0[1] * sigmoid_f(g0[1])); w.y = cvtpk(a0[2] * sigmoid_f(g0[2]), a0[3] * sigmoid_f(g0[3]));
;                     w.z = cvtpk(a1[0] * sigmoid_f(g1[0]), a1[1] * sigmoid_f(g1[1])); w.w = cvtpk(a1[2] * sigmoid_f(g1[2]), a1[3] * sigmoid_f(g1[3]));
;                     *(u32x4*)rowp = w;
;                 }
	v_mul_f32_e32 v133, 0xbfb8aa3b, v71
	v_exp_f32_e32 v133, v133
	v_cvt_pk_bf16_f32 v130, v130, v131
	v_add_f32_e32 v131, 1.0, v132
	v_rcp_f32_e32 v132, v131
	v_add_f32_e32 v131, 1.0, v133
	v_rcp_f32_e32 v133, v131
	v_mul_f32_e32 v131, 0xbfb8aa3b, v64
	v_exp_f32_e32 v131, v131
	v_pk_mul_f32 v[132:133], v[78:79], v[132:133]
	v_add_f32_e32 v131, 1.0, v131
	v_rcp_f32_e32 v136, v131
	v_add_f32_e32 v131, 1.0, v137
	v_mul_f32_e32 v137, 0xbfb8aa3b, v66
	v_exp_f32_e32 v138, v137
	v_mul_f32_e32 v137, 0xbfb8aa3b, v67
	v_exp_f32_e32 v139, v137
	v_rcp_f32_e32 v137, v131
	v_add_f32_e32 v131, 1.0, v138
	v_rcp_f32_e32 v138, v131
	v_add_f32_e32 v131, 1.0, v139
	v_rcp_f32_e32 v139, v131
	v_cvt_pk_bf16_f32 v131, v132, v133
	v_pk_mul_f32 v[132:133], v[72:73], v[136:137]
	v_pk_mul_f32 v[136:137], v[74:75], v[138:139]
	v_cvt_pk_bf16_f32 v132, v132, v133
	v_cvt_pk_bf16_f32 v133, v136, v137
	global_store_dwordx4 v[134:135], v[130:133], off sc1
	v_mul_f32_e32 v136, 0xbfb8aa3b, v49
	v_exp_f32_e32 v137, v136
	v_mul_f32_e32 v130, 0xbfb8aa3b, v52
	v_exp_f32_e32 v131, v130
	v_mul_f32_e32 v130, 0xbfb8aa3b, v53
	v_exp_f32_e32 v133, v130
	v_add_u32_e32 v130, s8, v193
	v_add_f32_e32 v131, 1.0, v131
	v_rcp_f32_e32 v132, v131
	v_add_f32_e32 v131, 1.0, v133
	v_rcp_f32_e32 v133, v131
	v_ashrrev_i32_e32 v131, 31, v130
	v_lshlrev_b64 v[130:131], 11, v[130:131]
	v_lshl_add_u64 v[134:135], v[128:129], 0, v[130:131]
	v_pk_mul_f32 v[130:131], v[60:61], v[132:133]
	v_mul_f32_e32 v132, 0xbfb8aa3b, v54
	v_exp_f32_e32 v132, v132
	v_mul_f32_e32 v133, 0xbfb8aa3b, v55
	v_exp_f32_e32 v133, v133
	v_cvt_pk_bf16_f32 v130, v130, v131
	v_add_f32_e32 v131, 1.0, v132
	v_rcp_f32_e32 v132, v131
	v_add_f32_e32 v131, 1.0, v133
	v_rcp_f32_e32 v133, v131
	v_mul_f32_e32 v131, 0xbfb8aa3b, v48
	v_exp_f32_e32 v131, v131
	v_pk_mul_f32 v[132:133], v[62:63], v[132:133]
	v_add_f32_e32 v131, 1.0, v131
	v_rcp_f32_e32 v136, v131
	v_add_f32_e32 v131, 1.0, v137
	v_mul_f32_e32 v137, 0xbfb8aa3b, v50
	v_exp_f32_e32 v138, v137
	v_mul_f32_e32 v137, 0xbfb8aa3b, v51
	v_exp_f32_e32 v139, v137
	v_rcp_f32_e32 v137, v131
	v_add_f32_e32 v131, 1.0, v138
	v_rcp_f32_e32 v138, v131
	v_add_f32_e32 v131, 1.0, v139
	v_rcp_f32_e32 v139, v131
	v_cvt_pk_bf16_f32 v131, v132, v133
	v_pk_mul_f32 v[132:133], v[56:57], v[136:137]
	v_pk_mul_f32 v[136:137], v[58:59], v[138:139]
	v_cvt_pk_bf16_f32 v132, v132, v133
	v_cvt_pk_bf16_f32 v133, v136, v137
	global_store_dwordx4 v[134:135], v[130:133], off sc1
	v_mul_f32_e32 v136, 0xbfb8aa3b, v33
	v_exp_f32_e32 v137, v136
	v_mul_f32_e32 v130, 0xbfb8aa3b, v36
	v_exp_f32_e32 v131, v130
	v_mul_f32_e32 v130, 0xbfb8aa3b, v37
	v_exp_f32_e32 v133, v130
	v_add_u32_e32 v130, s8, v194
	v_add_f32_e32 v131, 1.0, v131
	v_rcp_f32_e32 v132, v131
	v_add_f32_e32 v131, 1.0, v133
	v_rcp_f32_e32 v133, v131
	v_ashrrev_i32_e32 v131, 31, v130
	v_lshlrev_b64 v[130:131], 11, v[130:131]
	v_lshl_add_u64 v[134:135], v[128:129], 0, v[130:131]
	v_pk_mul_f32 v[130:131], v[44:45], v[132:133]
	v_mul_f32_e32 v132, 0xbfb8aa3b, v38
	v_exp_f32_e32 v132, v132
	v_mul_f32_e32 v133, 0xbfb8aa3b, v39
	v_exp_f32_e32 v133, v133
	v_cvt_pk_bf16_f32 v130, v130, v131
	v_add_f32_e32 v131, 1.0, v132
	v_rcp_f32_e32 v132, v131
	v_add_f32_e32 v131, 1.0, v133
	v_rcp_f32_e32 v133, v131
	v_mul_f32_e32 v131, 0xbfb8aa3b, v32
	v_exp_f32_e32 v131, v131
	v_pk_mul_f32 v[132:133], v[46:47], v[132:133]
	v_add_f32_e32 v131, 1.0, v131
	v_rcp_f32_e32 v136, v131
	v_add_f32_e32 v131, 1.0, v137
	v_mul_f32_e32 v137, 0xbfb8aa3b, v34
	v_exp_f32_e32 v138, v137
	v_mul_f32_e32 v137, 0xbfb8aa3b, v35
	v_exp_f32_e32 v139, v137
	v_rcp_f32_e32 v137, v131
	v_add_f32_e32 v131, 1.0, v138
	v_rcp_f32_e32 v138, v131
	v_add_f32_e32 v131, 1.0, v139
	v_rcp_f32_e32 v139, v131
	v_cvt_pk_bf16_f32 v131, v132, v133
	v_pk_mul_f32 v[132:133], v[40:41], v[136:137]
	v_pk_mul_f32 v[136:137], v[42:43], v[138:139]
	v_cvt_pk_bf16_f32 v132, v132, v133
	v_cvt_pk_bf16_f32 v133, v136, v137
	global_store_dwordx4 v[134:135], v[130:133], off sc1
	v_mul_f32_e32 v136, 0xbfb8aa3b, v17
	v_exp_f32_e32 v137, v136
	v_mul_f32_e32 v130, 0xbfb8aa3b, v20
	v_exp_f32_e32 v131, v130
	v_mul_f32_e32 v130, 0xbfb8aa3b, v21
	v_exp_f32_e32 v133, v130
	v_add_u32_e32 v130, s8, v195
	v_add_f32_e32 v131, 1.0, v131
	v_rcp_f32_e32 v132, v131
	v_add_f32_e32 v131, 1.0, v133
	v_rcp_f32_e32 v133, v131
	v_ashrrev_i32_e32 v131, 31, v130
	v_lshlrev_b64 v[130:131], 11, v[130:131]
	v_lshl_add_u64 v[134:135], v[128:129], 0, v[130:131]
	v_pk_mul_f32 v[130:131], v[28:29], v[132:133]
	v_mul_f32_e32 v132, 0xbfb8aa3b, v22
	v_exp_f32_e32 v132, v132
	v_mul_f32_e32 v133, 0xbfb8aa3b, v23
	v_exp_f32_e32 v133, v133
	v_cvt_pk_bf16_f32 v130, v130, v131
	v_add_f32_e32 v131, 1.0, v132
	v_rcp_f32_e32 v132, v131
	v_add_f32_e32 v131, 1.0, v133
	v_rcp_f32_e32 v133, v131
	v_mul_f32_e32 v131, 0xbfb8aa3b, v16
	v_exp_f32_e32 v131, v131
	v_pk_mul_f32 v[132:133], v[30:31], v[132:133]
	v_add_f32_e32 v131, 1.0, v131
	v_rcp_f32_e32 v136, v131
	v_add_f32_e32 v131, 1.0, v137
	v_mul_f32_e32 v137, 0xbfb8aa3b, v18
	v_exp_f32_e32 v138, v137
	v_mul_f32_e32 v137, 0xbfb8aa3b, v19
	v_exp_f32_e32 v139, v137
	v_rcp_f32_e32 v137, v131
	v_add_f32_e32 v131, 1.0, v138
	v_rcp_f32_e32 v138, v131
	v_add_f32_e32 v131, 1.0, v139
	v_rcp_f32_e32 v139, v131
	v_cvt_pk_bf16_f32 v131, v132, v133
	v_pk_mul_f32 v[132:133], v[24:25], v[136:137]
	v_pk_mul_f32 v[136:137], v[26:27], v[138:139]
	v_cvt_pk_bf16_f32 v132, v132, v133
	v_cvt_pk_bf16_f32 v133, v136, v137
	global_store_dwordx4 v[134:135], v[130:133], off sc1
	s_nop 1
	v_mul_f32_e32 v130, 0xbfb8aa3b, v4
	v_exp_f32_e32 v131, v130
	v_mul_f32_e32 v130, 0xbfb8aa3b, v5
	v_exp_f32_e32 v133, v130
	v_add_u32_e32 v130, s8, v196
	v_add_f32_e32 v131, 1.0, v131
	v_rcp_f32_e32 v132, v131
	v_add_f32_e32 v131, 1.0, v133
	v_rcp_f32_e32 v133, v131
	v_ashrrev_i32_e32 v131, 31, v130
	v_lshlrev_b64 v[130:131], 11, v[130:131]
	v_lshl_add_u64 v[134:135], v[128:129], 0, v[130:131]
	v_mul_f32_e32 v130, 0xbfb8aa3b, v6
	v_exp_f32_e32 v130, v130
	v_mul_f32_e32 v131, 0xbfb8aa3b, v7
	v_exp_f32_e32 v131, v131
	v_pk_mul_f32 v[128:129], v[12:13], v[132:133]
	v_mul_f32_e32 v132, 0xbfb8aa3b, v1
	v_cvt_pk_bf16_f32 v128, v128, v129
	v_add_f32_e32 v129, 1.0, v130
	v_rcp_f32_e32 v130, v129
	v_add_f32_e32 v129, 1.0, v131
	v_rcp_f32_e32 v131, v129
	v_mul_f32_e32 v129, 0xbfb8aa3b, v0
	v_exp_f32_e32 v129, v129
	v_exp_f32_e32 v133, v132
	v_pk_mul_f32 v[130:131], v[14:15], v[130:131]
	v_add_f32_e32 v129, 1.0, v129
	v_rcp_f32_e32 v132, v129
	v_add_f32_e32 v129, 1.0, v133
	v_mul_f32_e32 v133, 0xbfb8aa3b, v2
	v_exp_f32_e32 v136, v133
	v_mul_f32_e32 v133, 0xbfb8aa3b, v3
	v_exp_f32_e32 v137, v133
	v_rcp_f32_e32 v133, v129
	v_add_f32_e32 v129, 1.0, v136
	v_rcp_f32_e32 v136, v129
	v_add_f32_e32 v129, 1.0, v137
	v_rcp_f32_e32 v137, v129
	v_cvt_pk_bf16_f32 v129, v130, v131
	v_pk_mul_f32 v[130:131], v[8:9], v[132:133]
	v_pk_mul_f32 v[132:133], v[10:11], v[136:137]
	v_cvt_pk_bf16_f32 v130, v130, v131
	v_cvt_pk_bf16_f32 v131, v132, v133
	global_store_dwordx4 v[134:135], v[128:131], off sc1
	s_branch .LBB0_603

; __device__ __forceinline__ unsigned cvtpk(float lo, float hi) { f32x2 v = {lo, hi}; bf16x2_t b = __builtin_convertvector(v, bf16x2_t); return __builtin_bit_cast(unsigned, b); }
; __device__ __forceinline__ float silu_f(float v) { return v * __builtin_amdgcn_rcpf(1.0f + __builtin_amdgcn_exp2f(-v * LOG2E)); }
;     __device__ __forceinline__ void operator()(const f32x4 (&acc)[2][2][4][2], const pg8::Unit& u, int wr, int wc, int fr, int fq) const {
;     ...
;         } else if (kind == 1) {
;             const bool isa = u.pn < 12; const int pnl = isa ? (u.pn - 8) : (u.pn - 20);
;             bf16_t* dst = (bf16_t*)(ws + (isa ? WS_GA : WS_GC));
; #pragma unroll
;             for (int ai = 0; ai < 2; ++ai)
; #pragma unroll
;                 for (int m = 0; m < 4; ++m) {
;                     const int t = 256 * u.pm + 128 * ai + 64 * wr + 16 * m + fr;
;                     bf16_t* rowp = dst + (size_t)t * 1024 + 256 * pnl + 32 * wc + 8 * fq;
; #pragma unroll
;                     for (int bj = 0; bj < 2; ++bj) {
;                         const f32x4 v0 = acc[ai][bj][m][0], v1 = acc[ai][bj][m][1];
;                         u32x4 w; w.x = cvtpk(silu_f(v0[0]), silu_f(v0[1])); w.y = cvtpk(silu_f(v0[2]), silu_f(v0[3]));
;                         w.z = cvtpk(silu_f(v1[0]), silu_f(v1[1])); w.w = cvtpk(silu_f(v1[2]), silu_f(v1[3]));
;                         *(u32x4*)(rowp + 128 * bj) = w;
;                     }
;                 }
.LBB0_603:
	s_and_b64 vcc, exec, s[28:29]
	s_cbranch_vccz .LBB0_608
	s_cmp_gt_i32 s46, 0
	s_mov_b64 s[28:29], -1
	s_cbranch_scc0 .LBB0_606
	s_cmp_lt_i32 s68, 12
	s_cselect_b32 s28, -8, 0xffffffec
	s_cselect_b32 s8, s61, 0x9c00000
	s_add_i32 s28, s28, s68
	s_add_u32 s8, s44, s8
	s_addc_u32 s47, s45, 0
	s_lshl_b32 s28, s28, 8
	s_ashr_i32 s29, s28, 31
	s_lshl_b64 s[28:29], s[28:29], 1
	s_add_u32 s8, s8, s28
	s_addc_u32 s29, s47, s29
	s_lshl_b32 s28, s53, 1
	s_add_u32 s28, s8, s28
	v_mul_f32_e32 v132, 0xbfb8aa3b, v124
	v_mul_f32_e32 v133, 0xbfb8aa3b, v125
	s_addc_u32 s29, s29, 0
	s_lshl_b32 s8, s67, 8
	v_exp_f32_e32 v132, v132
	v_exp_f32_e32 v133, v133
	v_add_u32_e32 v130, s8, v169
	v_lshlrev_b32_e32 v166, 1, v164
	v_ashrrev_i32_e32 v131, 31, v130
	v_lshl_add_u64 v[128:129], s[28:29], 0, v[166:167]
	v_lshlrev_b64 v[130:131], 11, v[130:131]
	v_lshl_add_u64 v[134:135], v[128:129], 0, v[130:131]
	v_add_f32_e32 v130, 1.0, v132
	v_add_f32_e32 v131, 1.0, v133
	v_mul_f32_e32 v132, 0xbfb8aa3b, v126
	v_mul_f32_e32 v133, 0xbfb8aa3b, v127
	v_exp_f32_e32 v132, v132
	v_exp_f32_e32 v133, v133
	v_mul_f32_e32 v136, 0xbfb8aa3b, v120
	v_mul_f32_e32 v137, 0xbfb8aa3b, v121
	v_exp_f32_e32 v136, v136
	v_exp_f32_e32 v137, v137
	v_add_f32_e32 v132, 1.0, v132
	v_add_f32_e32 v133, 1.0, v133
	v_rcp_f32_e32 v130, v130
	v_rcp_f32_e32 v131, v131
	v_rcp_f32_e32 v132, v132
	v_rcp_f32_e32 v133, v133
	v_add_f32_e32 v136, 1.0, v136
	v_add_f32_e32 v137, 1.0, v137
	v_rcp_f32_e32 v136, v136
	v_rcp_f32_e32 v137, v137
	v_pk_mul_f32 v[130:131], v[124:125], v[130:131]
	v_pk_mul_f32 v[132:133], v[126:127], v[132:133]
	v_cvt_pk_bf16_f32 v130, v130, v131
	v_cvt_pk_bf16_f32 v131, v132, v133
	v_pk_mul_f32 v[132:133], v[120:121], v[136:137]
	v_mul_f32_e32 v136, 0xbfb8aa3b, v122
	v_exp_f32_e32 v136, v136
	v_mul_f32_e32 v137, 0xbfb8aa3b, v123
	v_exp_f32_e32 v137, v137
	v_cvt_pk_bf16_f32 v132, v132, v133
	v_add_f32_e32 v133, 1.0, v136
	v_rcp_f32_e32 v136, v133
	v_add_f32_e32 v133, 1.0, v137
	v_mul_f32_e32 v137, 0xbfb8aa3b, v116
	v_exp_f32_e32 v138, v137
	v_mul_f32_e32 v137, 0xbfb8aa3b, v117
	v_exp_f32_e32 v139, v137
	v_rcp_f32_e32 v137, v133
	v_add_f32_e32 v133, 1.0, v138
	v_rcp_f32_e32 v138, v133
	v_add_f32_e32 v133, 1.0, v139
	v_pk_mul_f32 v[136:137], v[122:123], v[136:137]
	v_rcp_f32_e32 v139, v133
	v_cvt_pk_bf16_f32 v133, v136, v137
	global_store_dwordx4 v[134:135], v[130:133], off sc1
	v_mul_f32_e32 v136, 0xbfb8aa3b, v113
	v_exp_f32_e32 v137, v136
	v_mul_f32_e32 v132, 0xbfb8aa3b, v118
	v_exp_f32_e32 v132, v132
	v_mul_f32_e32 v133, 0xbfb8aa3b, v119
	v_exp_f32_e32 v133, v133
	v_pk_mul_f32 v[130:131], v[116:117], v[138:139]
	s_mov_b64 s[28:29], 0
	v_cvt_pk_bf16_f32 v130, v130, v131
	v_add_f32_e32 v131, 1.0, v132
	v_rcp_f32_e32 v132, v131
	v_add_f32_e32 v131, 1.0, v133
	v_rcp_f32_e32 v133, v131
	v_mul_f32_e32 v131, 0xbfb8aa3b, v112
	v_exp_f32_e32 v131, v131
	v_pk_mul_f32 v[132:133], v[118:119], v[132:133]
	v_add_f32_e32 v131, 1.0, v131
	v_rcp_f32_e32 v136, v131
	v_add_f32_e32 v131, 1.0, v137
	v_mul_f32_e32 v137, 0xbfb8aa3b, v114
	v_exp_f32_e32 v138, v137
	v_mul_f32_e32 v137, 0xbfb8aa3b, v115
	v_exp_f32_e32 v139, v137
	v_rcp_f32_e32 v137, v131
	v_add_f32_e32 v131, 1.0, v138
	v_rcp_f32_e32 v138, v131
	v_add_f32_e32 v131, 1.0, v139
	v_rcp_f32_e32 v139, v131
	v_cvt_pk_bf16_f32 v131, v132, v133
	v_pk_mul_f32 v[132:133], v[112:113], v[136:137]
	v_pk_mul_f32 v[136:137], v[114:115], v[138:139]
	v_cvt_pk_bf16_f32 v132, v132, v133
	v_cvt_pk_bf16_f32 v133, v136, v137
	global_store_dwordx4 v[134:135], v[130:133], off offset:256 sc1
	v_mul_f32_e32 v136, 0xbfb8aa3b, v104
	v_mul_f32_e32 v137, 0xbfb8aa3b, v105
	v_mul_f32_e32 v132, 0xbfb8aa3b, v108
	v_mul_f32_e32 v133, 0xbfb8aa3b, v109
	v_exp_f32_e32 v132, v132
	v_exp_f32_e32 v133, v133
	v_add_u32_e32 v130, s8, v190
	v_ashrrev_i32_e32 v131, 31, v130
	v_lshlrev_b64 v[130:131], 11, v[130:131]
	v_lshl_add_u64 v[134:135], v[128:129], 0, v[130:131]
	v_add_f32_e32 v130, 1.0, v132
	v_add_f32_e32 v131, 1.0, v133
	v_mul_f32_e32 v132, 0xbfb8aa3b, v110
	v_mul_f32_e32 v133, 0xbfb8aa3b, v111
	v_exp_f32_e32 v132, v132
	v_exp_f32_e32 v133, v133
	v_exp_f32_e32 v136, v136
	v_exp_f32_e32 v137, v137
	v_add_f32_e32 v132, 1.0, v132
	v_add_f32_e32 v133, 1.0, v133
	v_rcp_f32_e32 v130, v130
	v_rcp_f32_e32 v131, v131
	v_rcp_f32_e32 v132, v132
	v_rcp_f32_e32 v133, v133
	v_add_f32_e32 v136, 1.0, v136
	v_add_f32_e32 v137, 1.0, v137
	v_rcp_f32_e32 v136, v136
	v_rcp_f32_e32 v137, v137
	v_pk_mul_f32 v[130:131], v[108:109], v[130:131]
	v_pk_mul_f32 v[132:133], v[110:111], v[132:133]
	v_cvt_pk_bf16_f32 v130, v130, v131
	v_cvt_pk_bf16_f32 v131, v132, v133
	v_pk_mul_f32 v[132:133], v[104:105], v[136:137]
	v_mul_f32_e32 v136, 0xbfb8aa3b, v106
	v_exp_f32_e32 v136, v136
	v_mul_f32_e32 v137, 0xbfb8aa3b, v107
	v_exp_f32_e32 v137, v137
	v_cvt_pk_bf16_f32 v132, v132, v133
	v_add_f32_e32 v133, 1.0, v136
	v_rcp_f32_e32 v136, v133
	v_add_f32_e32 v133, 1.0, v137
	v_mul_f32_e32 v137, 0xbfb8aa3b, v100
	v_exp_f32_e32 v138, v137
	v_mul_f32_e32 v137, 0xbfb8aa3b, v101
	v_exp_f32_e32 v139, v137
	v_rcp_f32_e32 v137, v133
	v_add_f32_e32 v133, 1.0, v138
	v_rcp_f32_e32 v138, v133
	v_add_f32_e32 v133, 1.0, v139
	v_pk_mul_f32 v[136:137], v[106:107], v[136:137]
	v_rcp_f32_e32 v139, v133
	v_cvt_pk_bf16_f32 v133, v136, v137
	global_store_dwordx4 v[134:135], v[130:133], off sc1
	v_mul_f32_e32 v136, 0xbfb8aa3b, v97
	v_exp_f32_e32 v137, v136
	v_mul_f32_e32 v132, 0xbfb8aa3b, v102
	v_exp_f32_e32 v132, v132
	v_mul_f32_e32 v133, 0xbfb8aa3b, v103
	v_exp_f32_e32 v133, v133
	v_pk_mul_f32 v[130:131], v[100:101], v[138:139]
	s_nop 0
	v_cvt_pk_bf16_f32 v130, v130, v131
	v_add_f32_e32 v131, 1.0, v132
	v_rcp_f32_e32 v132, v131
; __device__ __forceinline__ unsigned cvtpk(float lo, float hi) { f32x2 v = {lo, hi}; bf16x2_t b = __builtin_convertvector(v, bf16x2_t); return __builtin_bit_cast(unsigned, b); }
; __device__ __forceinline__ float silu_f(float v) { return v * __builtin_amdgcn_rcpf(1.0f + __builtin_amdgcn_exp2f(-v * LOG2E)); }
;     __device__ __forceinline__ void operator()(const f32x4 (&acc)[2][2][4][2], const pg8::Unit& u, int wr, int wc, int fr, int fq) const {
;     ...
;         } else if (kind == 1) {
;             const bool isa = u.pn < 12; const int pnl = isa ? (u.pn - 8) : (u.pn - 20);
;             bf16_t* dst = (bf16_t*)(ws + (isa ? WS_GA : WS_GC));
; #pragma unroll
;             for (int ai = 0; ai < 2; ++ai)
; #pragma unroll
;                 for (int m = 0; m < 4; ++m) {
;                     const int t = 256 * u.pm + 128 * ai + 64 * wr + 16 * m + fr;
;                     bf16_t* rowp = dst + (size_t)t * 1024 + 256 * pnl + 32 * wc + 8 * fq;
; #pragma unroll
;                     for (int bj = 0; bj < 2; ++bj) {
;                         const f32x4 v0 = acc[ai][bj][m][0], v1 = acc[ai][bj][m][1];
;                         u32x4 w; w.x = cvtpk(silu_f(v0[0]), silu_f(v0[1])); w.y = cvtpk(silu_f(v0[2]), silu_f(v0[3]));
;                         w.z = cvtpk(silu_f(v1[0]), silu_f(v1[1])); w.w = cvtpk(silu_f(v1[2]), silu_f(v1[3]));
;                         *(u32x4*)(rowp + 128 * bj) = w;
;                     }
;                 }
	v_add_f32_e32 v131, 1.0, v133
	v_rcp_f32_e32 v133, v131
	v_mul_f32_e32 v131, 0xbfb8aa3b, v96
	v_exp_f32_e32 v131, v131
	v_pk_mul_f32 v[132:133], v[102:103], v[132:133]
	v_add_f32_e32 v131, 1.0, v131
	v_rcp_f32_e32 v136, v131
	v_add_f32_e32 v131, 1.0, v137
	v_mul_f32_e32 v137, 0xbfb8aa3b, v98
	v_exp_f32_e32 v138, v137
	v_mul_f32_e32 v137, 0xbfb8aa3b, v99
	v_exp_f32_e32 v139, v137
	v_rcp_f32_e32 v137, v131
	v_add_f32_e32 v131, 1.0, v138
	v_rcp_f32_e32 v138, v131
	v_add_f32_e32 v131, 1.0, v139
	v_rcp_f32_e32 v139, v131
	v_cvt_pk_bf16_f32 v131, v132, v133
	v_pk_mul_f32 v[132:133], v[96:97], v[136:137]
	v_pk_mul_f32 v[136:137], v[98:99], v[138:139]
	v_cvt_pk_bf16_f32 v132, v132, v133
	v_cvt_pk_bf16_f32 v133, v136, v137
	global_store_dwordx4 v[134:135], v[130:133], off offset:256 sc1
	v_mul_f32_e32 v136, 0xbfb8aa3b, v88
	v_mul_f32_e32 v137, 0xbfb8aa3b, v89
	v_mul_f32_e32 v132, 0xbfb8aa3b, v92
	v_mul_f32_e32 v133, 0xbfb8aa3b, v93
	v_exp_f32_e32 v132, v132
	v_exp_f32_e32 v133, v133
	v_add_u32_e32 v130, s8, v191
	v_ashrrev_i32_e32 v131, 31, v130
	v_lshlrev_b64 v[130:131], 11, v[130:131]
	v_lshl_add_u64 v[134:135], v[128:129], 0, v[130:131]
	v_add_f32_e32 v130, 1.0, v132
	v_add_f32_e32 v131, 1.0, v133
	v_mul_f32_e32 v132, 0xbfb8aa3b, v94
	v_mul_f32_e32 v133, 0xbfb8aa3b, v95
	v_exp_f32_e32 v132, v132
	v_exp_f32_e32 v133, v133
	v_exp_f32_e32 v136, v136
	v_exp_f32_e32 v137, v137
	v_add_f32_e32 v132, 1.0, v132
	v_add_f32_e32 v133, 1.0, v133
	v_rcp_f32_e32 v130, v130
	v_rcp_f32_e32 v131, v131
	v_rcp_f32_e32 v132, v132
	v_rcp_f32_e32 v133, v133
	v_add_f32_e32 v136, 1.0, v136
	v_add_f32_e32 v137, 1.0, v137
	v_rcp_f32_e32 v136, v136
	v_rcp_f32_e32 v137, v137
	v_pk_mul_f32 v[130:131], v[92:93], v[130:131]
	v_pk_mul_f32 v[132:133], v[94:95], v[132:133]
	v_cvt_pk_bf16_f32 v130, v130, v131
	v_cvt_pk_bf16_f32 v131, v132, v133
	v_pk_mul_f32 v[132:133], v[88:89], v[136:137]
	v_mul_f32_e32 v136, 0xbfb8aa3b, v90
	v_exp_f32_e32 v136, v136
	v_mul_f32_e32 v137, 0xbfb8aa3b, v91
	v_exp_f32_e32 v137, v137
	v_cvt_pk_bf16_f32 v132, v132, v133
	v_add_f32_e32 v133, 1.0, v136
	v_rcp_f32_e32 v136, v133
	v_add_f32_e32 v133, 1.0, v137
	v_mul_f32_e32 v137, 0xbfb8aa3b, v84
	v_exp_f32_e32 v138, v137
	v_mul_f32_e32 v137, 0xbfb8aa3b, v85
	v_exp_f32_e32 v139, v137
	v_rcp_f32_e32 v137, v133
	v_add_f32_e32 v133, 1.0, v138
	v_rcp_f32_e32 v138, v133
	v_add_f32_e32 v133, 1.0, v139
	v_pk_mul_f32 v[136:137], v[90:91], v[136:137]
	v_rcp_f32_e32 v139, v133
	v_cvt_pk_bf16_f32 v133, v136, v137
	global_store_dwordx4 v[134:135], v[130:133], off sc1
	v_mul_f32_e32 v136, 0xbfb8aa3b, v81
	v_exp_f32_e32 v137, v136
	v_mul_f32_e32 v132, 0xbfb8aa3b, v86
	v_exp_f32_e32 v132, v132
	v_mul_f32_e32 v133, 0xbfb8aa3b, v87
	v_exp_f32_e32 v133, v133
	v_pk_mul_f32 v[130:131], v[84:85], v[138:139]
	s_nop 0
	v_cvt_pk_bf16_f32 v130, v130, v131
	v_add_f32_e32 v131, 1.0, v132
	v_rcp_f32_e32 v132, v131
	v_add_f32_e32 v131, 1.0, v133
	v_rcp_f32_e32 v133, v131
	v_mul_f32_e32 v131, 0xbfb8aa3b, v80
	v_exp_f32_e32 v131, v131
	v_pk_mul_f32 v[132:133], v[86:87], v[132:133]
	v_add_f32_e32 v131, 1.0, v131
	v_rcp_f32_e32 v136, v131
	v_add_f32_e32 v131, 1.0, v137
	v_mul_f32_e32 v137, 0xbfb8aa3b, v82
	v_exp_f32_e32 v138, v137
	v_mul_f32_e32 v137, 0xbfb8aa3b, v83
	v_exp_f32_e32 v139, v137
	v_rcp_f32_e32 v137, v131
	v_add_f32_e32 v131, 1.0, v138
	v_rcp_f32_e32 v138, v131
	v_add_f32_e32 v131, 1.0, v139
	v_rcp_f32_e32 v139, v131
	v_cvt_pk_bf16_f32 v131, v132, v133
	v_pk_mul_f32 v[132:133], v[80:81], v[136:137]
	v_pk_mul_f32 v[136:137], v[82:83], v[138:139]
	v_cvt_pk_bf16_f32 v132, v132, v133
	v_cvt_pk_bf16_f32 v133, v136, v137
	global_store_dwordx4 v[134:135], v[130:133], off offset:256 sc1
	v_mul_f32_e32 v136, 0xbfb8aa3b, v72
	v_mul_f32_e32 v137, 0xbfb8aa3b, v73
	v_mul_f32_e32 v132, 0xbfb8aa3b, v76
	v_mul_f32_e32 v133, 0xbfb8aa3b, v77
	v_exp_f32_e32 v132, v132
	v_exp_f32_e32 v133, v133
	v_add_u32_e32 v130, s8, v192
	v_ashrrev_i32_e32 v131, 31, v130
	v_lshlrev_b64 v[130:131], 11, v[130:131]
	v_lshl_add_u64 v[134:135], v[128:129], 0, v[130:131]
	v_add_f32_e32 v130, 1.0, v132
	v_add_f32_e32 v131, 1.0, v133
	v_mul_f32_e32 v132, 0xbfb8aa3b, v78
	v_mul_f32_e32 v133, 0xbfb8aa3b, v79
	v_exp_f32_e32 v132, v132
	v_exp_f32_e32 v133, v133
	v_exp_f32_e32 v136, v136
	v_exp_f32_e32 v137, v137
	v_add_f32_e32 v132, 1.0, v132
	v_add_f32_e32 v133, 1.0, v133
	v_rcp_f32_e32 v130, v130
	v_rcp_f32_e32 v131, v131
	v_rcp_f32_e32 v132, v132
	v_rcp_f32_e32 v133, v133
	v_add_f32_e32 v136, 1.0, v136
	v_add_f32_e32 v137, 1.0, v137
	v_rcp_f32_e32 v136, v136
	v_rcp_f32_e32 v137, v137
	v_pk_mul_f32 v[130:131], v[76:77], v[130:131]
	v_pk_mul_f32 v[132:133], v[78:79], v[132:133]
	v_cvt_pk_bf16_f32 v130, v130, v131
	v_cvt_pk_bf16_f32 v131, v132, v133
	v_pk_mul_f32 v[132:133], v[72:73], v[136:137]
	v_mul_f32_e32 v136, 0xbfb8aa3b, v74
	v_exp_f32_e32 v136, v136
	v_mul_f32_e32 v137, 0xbfb8aa3b, v75
	v_exp_f32_e32 v137, v137
	v_cvt_pk_bf16_f32 v132, v132, v133
	v_add_f32_e32 v133, 1.0, v136
	v_rcp_f32_e32 v136, v133
	v_add_f32_e32 v133, 1.0, v137
	v_mul_f32_e32 v137, 0xbfb8aa3b, v68
	v_exp_f32_e32 v138, v137
	v_mul_f32_e32 v137, 0xbfb8aa3b, v69
	v_exp_f32_e32 v139, v137
	v_rcp_f32_e32 v137, v133
	v_add_f32_e32 v133, 1.0, v138
	v_rcp_f32_e32 v138, v133
	v_add_f32_e32 v133, 1.0, v139
	v_pk_mul_f32 v[136:137], v[74:75], v[136:137]
	v_rcp_f32_e32 v139, v133
	v_cvt_pk_bf16_f32 v133, v136, v137
	global_store_dwordx4 v[134:135], v[130:133], off sc1
	v_mul_f32_e32 v136, 0xbfb8aa3b, v65
	v_exp_f32_e32 v137, v136
	v_mul_f32_e32 v132, 0xbfb8aa3b, v70
	v_exp_f32_e32 v132, v132
	v_mul_f32_e32 v133, 0xbfb8aa3b, v71
	v_exp_f32_e32 v133, v133
	v_pk_mul_f32 v[130:131], v[68:69], v[138:139]
; __device__ __forceinline__ unsigned cvtpk(float lo, float hi) { f32x2 v = {lo, hi}; bf16x2_t b = __builtin_convertvector(v, bf16x2_t); return __builtin_bit_cast(unsigned, b); }
; __device__ __forceinline__ float silu_f(float v) { return v * __builtin_amdgcn_rcpf(1.0f + __builtin_amdgcn_exp2f(-v * LOG2E)); }
;     __device__ __forceinline__ void operator()(const f32x4 (&acc)[2][2][4][2], const pg8::Unit& u, int wr, int wc, int fr, int fq) const {
;     ...
;         } else if (kind == 1) {
;             const bool isa = u.pn < 12; const int pnl = isa ? (u.pn - 8) : (u.pn - 20);
;             bf16_t* dst = (bf16_t*)(ws + (isa ? WS_GA : WS_GC));
; #pragma unroll
;             for (int ai = 0; ai < 2; ++ai)
; #pragma unroll
;                 for (int m = 0; m < 4; ++m) {
;                     const int t = 256 * u.pm + 128 * ai + 64 * wr + 16 * m + fr;
;                     bf16_t* rowp = dst + (size_t)t * 1024 + 256 * pnl + 32 * wc + 8 * fq;
; #pragma unroll
;                     for (int bj = 0; bj < 2; ++bj) {
;                         const f32x4 v0 = acc[ai][bj][m][0], v1 = acc[ai][bj][m][1];
;                         u32x4 w; w.x = cvtpk(silu_f(v0[0]), silu_f(v0[1])); w.y = cvtpk(silu_f(v0[2]), silu_f(v0[3]));
;                         w.z = cvtpk(silu_f(v1[0]), silu_f(v1[1])); w.w = cvtpk(silu_f(v1[2]), silu_f(v1[3]));
;                         *(u32x4*)(rowp + 128 * bj) = w;
;                     }
;                 }
	s_nop 0
	v_cvt_pk_bf16_f32 v130, v130, v131
	v_add_f32_e32 v131, 1.0, v132
	v_rcp_f32_e32 v132, v131
	v_add_f32_e32 v131, 1.0, v133
	v_rcp_f32_e32 v133, v131
	v_mul_f32_e32 v131, 0xbfb8aa3b, v64
	v_exp_f32_e32 v131, v131
	v_pk_mul_f32 v[132:133], v[70:71], v[132:133]
	v_add_f32_e32 v131, 1.0, v131
	v_rcp_f32_e32 v136, v131
	v_add_f32_e32 v131, 1.0, v137
	v_mul_f32_e32 v137, 0xbfb8aa3b, v66
	v_exp_f32_e32 v138, v137
	v_mul_f32_e32 v137, 0xbfb8aa3b, v67
	v_exp_f32_e32 v139, v137
	v_rcp_f32_e32 v137, v131
	v_add_f32_e32 v131, 1.0, v138
	v_rcp_f32_e32 v138, v131
	v_add_f32_e32 v131, 1.0, v139
	v_rcp_f32_e32 v139, v131
	v_cvt_pk_bf16_f32 v131, v132, v133
	v_pk_mul_f32 v[132:133], v[64:65], v[136:137]
	v_pk_mul_f32 v[136:137], v[66:67], v[138:139]
	v_cvt_pk_bf16_f32 v132, v132, v133
	v_cvt_pk_bf16_f32 v133, v136, v137
	global_store_dwordx4 v[134:135], v[130:133], off offset:256 sc1
	v_mul_f32_e32 v136, 0xbfb8aa3b, v56
	v_mul_f32_e32 v137, 0xbfb8aa3b, v57
	v_mul_f32_e32 v132, 0xbfb8aa3b, v60
	v_mul_f32_e32 v133, 0xbfb8aa3b, v61
	v_exp_f32_e32 v132, v132
	v_exp_f32_e32 v133, v133
	v_add_u32_e32 v130, s8, v193
	v_ashrrev_i32_e32 v131, 31, v130
	v_lshlrev_b64 v[130:131], 11, v[130:131]
	v_lshl_add_u64 v[134:135], v[128:129], 0, v[130:131]
	v_add_f32_e32 v130, 1.0, v132
	v_add_f32_e32 v131, 1.0, v133
	v_mul_f32_e32 v132, 0xbfb8aa3b, v62
	v_mul_f32_e32 v133, 0xbfb8aa3b, v63
	v_exp_f32_e32 v132, v132
	v_exp_f32_e32 v133, v133
	v_exp_f32_e32 v136, v136
	v_exp_f32_e32 v137, v137
	v_add_f32_e32 v132, 1.0, v132
	v_add_f32_e32 v133, 1.0, v133
	v_rcp_f32_e32 v130, v130
	v_rcp_f32_e32 v131, v131
	v_rcp_f32_e32 v132, v132
	v_rcp_f32_e32 v133, v133
	v_add_f32_e32 v136, 1.0, v136
	v_add_f32_e32 v137, 1.0, v137
	v_rcp_f32_e32 v136, v136
	v_rcp_f32_e32 v137, v137
	v_pk_mul_f32 v[130:131], v[60:61], v[130:131]
	v_pk_mul_f32 v[132:133], v[62:63], v[132:133]
	v_cvt_pk_bf16_f32 v130, v130, v131
	v_cvt_pk_bf16_f32 v131, v132, v133
	v_pk_mul_f32 v[132:133], v[56:57], v[136:137]
	v_mul_f32_e32 v136, 0xbfb8aa3b, v58
	v_exp_f32_e32 v136, v136
	v_mul_f32_e32 v137, 0xbfb8aa3b, v59
	v_exp_f32_e32 v137, v137
	v_cvt_pk_bf16_f32 v132, v132, v133
	v_add_f32_e32 v133, 1.0, v136
	v_rcp_f32_e32 v136, v133
	v_add_f32_e32 v133, 1.0, v137
	v_mul_f32_e32 v137, 0xbfb8aa3b, v52
	v_exp_f32_e32 v138, v137
	v_mul_f32_e32 v137, 0xbfb8aa3b, v53
	v_exp_f32_e32 v139, v137
	v_rcp_f32_e32 v137, v133
	v_add_f32_e32 v133, 1.0, v138
	v_rcp_f32_e32 v138, v133
	v_add_f32_e32 v133, 1.0, v139
	v_pk_mul_f32 v[136:137], v[58:59], v[136:137]
	v_rcp_f32_e32 v139, v133
	v_cvt_pk_bf16_f32 v133, v136, v137
	global_store_dwordx4 v[134:135], v[130:133], off sc1
	v_mul_f32_e32 v136, 0xbfb8aa3b, v49
	v_exp_f32_e32 v137, v136
	v_mul_f32_e32 v132, 0xbfb8aa3b, v54
	v_exp_f32_e32 v132, v132
	v_mul_f32_e32 v133, 0xbfb8aa3b, v55
	v_exp_f32_e32 v133, v133
	v_pk_mul_f32 v[130:131], v[52:53], v[138:139]
	s_nop 0
	v_cvt_pk_bf16_f32 v130, v130, v131
	v_add_f32_e32 v131, 1.0, v132
	v_rcp_f32_e32 v132, v131
	v_add_f32_e32 v131, 1.0, v133
	v_rcp_f32_e32 v133, v131
	v_mul_f32_e32 v131, 0xbfb8aa3b, v48
	v_exp_f32_e32 v131, v131
	v_pk_mul_f32 v[132:133], v[54:55], v[132:133]
	v_add_f32_e32 v131, 1.0, v131
	v_rcp_f32_e32 v136, v131
	v_add_f32_e32 v131, 1.0, v137
	v_mul_f32_e32 v137, 0xbfb8aa3b, v50
	v_exp_f32_e32 v138, v137
	v_mul_f32_e32 v137, 0xbfb8aa3b, v51
	v_exp_f32_e32 v139, v137
	v_rcp_f32_e32 v137, v131
	v_add_f32_e32 v131, 1.0, v138
	v_rcp_f32_e32 v138, v131
	v_add_f32_e32 v131, 1.0, v139
	v_rcp_f32_e32 v139, v131
	v_cvt_pk_bf16_f32 v131, v132, v133
	v_pk_mul_f32 v[132:133], v[48:49], v[136:137]
	v_pk_mul_f32 v[136:137], v[50:51], v[138:139]
	v_cvt_pk_bf16_f32 v132, v132, v133
	v_cvt_pk_bf16_f32 v133, v136, v137
	global_store_dwordx4 v[134:135], v[130:133], off offset:256 sc1
	v_mul_f32_e32 v136, 0xbfb8aa3b, v40
	v_mul_f32_e32 v137, 0xbfb8aa3b, v41
	v_mul_f32_e32 v132, 0xbfb8aa3b, v44
	v_mul_f32_e32 v133, 0xbfb8aa3b, v45
	v_exp_f32_e32 v132, v132
	v_exp_f32_e32 v133, v133
	v_add_u32_e32 v130, s8, v194
	v_ashrrev_i32_e32 v131, 31, v130
	v_lshlrev_b64 v[130:131], 11, v[130:131]
	v_lshl_add_u64 v[134:135], v[128:129], 0, v[130:131]
	v_add_f32_e32 v130, 1.0, v132
	v_add_f32_e32 v131, 1.0, v133
	v_mul_f32_e32 v132, 0xbfb8aa3b, v46
	v_mul_f32_e32 v133, 0xbfb8aa3b, v47
	v_exp_f32_e32 v132, v132
	v_exp_f32_e32 v133, v133
	v_exp_f32_e32 v136, v136
	v_exp_f32_e32 v137, v137
	v_add_f32_e32 v132, 1.0, v132
	v_add_f32_e32 v133, 1.0, v133
	v_rcp_f32_e32 v130, v130
	v_rcp_f32_e32 v131, v131
	v_rcp_f32_e32 v132, v132
	v_rcp_f32_e32 v133, v133
	v_add_f32_e32 v136, 1.0, v136
	v_add_f32_e32 v137, 1.0, v137
	v_rcp_f32_e32 v136, v136
	v_rcp_f32_e32 v137, v137
	v_pk_mul_f32 v[130:131], v[44:45], v[130:131]
	v_pk_mul_f32 v[132:133], v[46:47], v[132:133]
	v_cvt_pk_bf16_f32 v130, v130, v131
	v_cvt_pk_bf16_f32 v131, v132, v133
	v_pk_mul_f32 v[132:133], v[40:41], v[136:137]
	v_mul_f32_e32 v136, 0xbfb8aa3b, v42
	v_exp_f32_e32 v136, v136
	v_mul_f32_e32 v137, 0xbfb8aa3b, v43
	v_exp_f32_e32 v137, v137
	v_cvt_pk_bf16_f32 v132, v132, v133
	v_add_f32_e32 v133, 1.0, v136
	v_rcp_f32_e32 v136, v133
	v_add_f32_e32 v133, 1.0, v137
	v_mul_f32_e32 v137, 0xbfb8aa3b, v36
	v_exp_f32_e32 v138, v137
	v_mul_f32_e32 v137, 0xbfb8aa3b, v37
	v_exp_f32_e32 v139, v137
	v_rcp_f32_e32 v137, v133
	v_add_f32_e32 v133, 1.0, v138
	v_rcp_f32_e32 v138, v133
	v_add_f32_e32 v133, 1.0, v139
	v_pk_mul_f32 v[136:137], v[42:43], v[136:137]
	v_rcp_f32_e32 v139, v133
	v_cvt_pk_bf16_f32 v133, v136, v137
	global_store_dwordx4 v[134:135], v[130:133], off sc1
	v_mul_f32_e32 v136, 0xbfb8aa3b, v33
	v_exp_f32_e32 v137, v136
	v_mul_f32_e32 v132, 0xbfb8aa3b, v38
	v_exp_f32_e32 v132, v132
; __device__ __forceinline__ unsigned cvtpk(float lo, float hi) { f32x2 v = {lo, hi}; bf16x2_t b = __builtin_convertvector(v, bf16x2_t); return __builtin_bit_cast(unsigned, b); }
; __device__ __forceinline__ float silu_f(float v) { return v * __builtin_amdgcn_rcpf(1.0f + __builtin_amdgcn_exp2f(-v * LOG2E)); }
;     __device__ __forceinline__ void operator()(const f32x4 (&acc)[2][2][4][2], const pg8::Unit& u, int wr, int wc, int fr, int fq) const {
;     ...
;         } else if (kind == 1) {
;             const bool isa = u.pn < 12; const int pnl = isa ? (u.pn - 8) : (u.pn - 20);
;             bf16_t* dst = (bf16_t*)(ws + (isa ? WS_GA : WS_GC));
; #pragma unroll
;             for (int ai = 0; ai < 2; ++ai)
; #pragma unroll
;                 for (int m = 0; m < 4; ++m) {
;                     const int t = 256 * u.pm + 128 * ai + 64 * wr + 16 * m + fr;
;                     bf16_t* rowp = dst + (size_t)t * 1024 + 256 * pnl + 32 * wc + 8 * fq;
; #pragma unroll
;                     for (int bj = 0; bj < 2; ++bj) {
;                         const f32x4 v0 = acc[ai][bj][m][0], v1 = acc[ai][bj][m][1];
;                         u32x4 w; w.x = cvtpk(silu_f(v0[0]), silu_f(v0[1])); w.y = cvtpk(silu_f(v0[2]), silu_f(v0[3]));
;                         w.z = cvtpk(silu_f(v1[0]), silu_f(v1[1])); w.w = cvtpk(silu_f(v1[2]), silu_f(v1[3]));
;                         *(u32x4*)(rowp + 128 * bj) = w;
;                     }
;                 }
	v_mul_f32_e32 v133, 0xbfb8aa3b, v39
	v_exp_f32_e32 v133, v133
	v_pk_mul_f32 v[130:131], v[36:37], v[138:139]
	s_nop 0
	v_cvt_pk_bf16_f32 v130, v130, v131
	v_add_f32_e32 v131, 1.0, v132
	v_rcp_f32_e32 v132, v131
	v_add_f32_e32 v131, 1.0, v133
	v_rcp_f32_e32 v133, v131
	v_mul_f32_e32 v131, 0xbfb8aa3b, v32
	v_exp_f32_e32 v131, v131
	v_pk_mul_f32 v[132:133], v[38:39], v[132:133]
	v_add_f32_e32 v131, 1.0, v131
	v_rcp_f32_e32 v136, v131
	v_add_f32_e32 v131, 1.0, v137
	v_mul_f32_e32 v137, 0xbfb8aa3b, v34
	v_exp_f32_e32 v138, v137
	v_mul_f32_e32 v137, 0xbfb8aa3b, v35
	v_exp_f32_e32 v139, v137
	v_rcp_f32_e32 v137, v131
	v_add_f32_e32 v131, 1.0, v138
	v_rcp_f32_e32 v138, v131
	v_add_f32_e32 v131, 1.0, v139
	v_rcp_f32_e32 v139, v131
	v_cvt_pk_bf16_f32 v131, v132, v133
	v_pk_mul_f32 v[132:133], v[32:33], v[136:137]
	v_pk_mul_f32 v[136:137], v[34:35], v[138:139]
	v_cvt_pk_bf16_f32 v132, v132, v133
	v_cvt_pk_bf16_f32 v133, v136, v137
	global_store_dwordx4 v[134:135], v[130:133], off offset:256 sc1
	v_mul_f32_e32 v136, 0xbfb8aa3b, v24
	v_mul_f32_e32 v137, 0xbfb8aa3b, v25
	v_mul_f32_e32 v132, 0xbfb8aa3b, v28
	v_mul_f32_e32 v133, 0xbfb8aa3b, v29
	v_exp_f32_e32 v132, v132
	v_exp_f32_e32 v133, v133
	v_add_u32_e32 v130, s8, v195
	v_ashrrev_i32_e32 v131, 31, v130
	v_lshlrev_b64 v[130:131], 11, v[130:131]
	v_lshl_add_u64 v[134:135], v[128:129], 0, v[130:131]
	v_add_f32_e32 v130, 1.0, v132
	v_add_f32_e32 v131, 1.0, v133
	v_mul_f32_e32 v132, 0xbfb8aa3b, v30
	v_mul_f32_e32 v133, 0xbfb8aa3b, v31
	v_exp_f32_e32 v132, v132
	v_exp_f32_e32 v133, v133
	v_exp_f32_e32 v136, v136
	v_exp_f32_e32 v137, v137
	v_add_f32_e32 v132, 1.0, v132
	v_add_f32_e32 v133, 1.0, v133
	v_rcp_f32_e32 v130, v130
	v_rcp_f32_e32 v131, v131
	v_rcp_f32_e32 v132, v132
	v_rcp_f32_e32 v133, v133
	v_add_f32_e32 v136, 1.0, v136
	v_add_f32_e32 v137, 1.0, v137
	v_rcp_f32_e32 v136, v136
	v_rcp_f32_e32 v137, v137
	v_pk_mul_f32 v[130:131], v[28:29], v[130:131]
	v_pk_mul_f32 v[132:133], v[30:31], v[132:133]
	v_cvt_pk_bf16_f32 v130, v130, v131
	v_cvt_pk_bf16_f32 v131, v132, v133
	v_pk_mul_f32 v[132:133], v[24:25], v[136:137]
	v_mul_f32_e32 v136, 0xbfb8aa3b, v26
	v_exp_f32_e32 v136, v136
	v_mul_f32_e32 v137, 0xbfb8aa3b, v27
	v_exp_f32_e32 v137, v137
	v_cvt_pk_bf16_f32 v132, v132, v133
	v_add_f32_e32 v133, 1.0, v136
	v_rcp_f32_e32 v136, v133
	v_add_f32_e32 v133, 1.0, v137
	v_mul_f32_e32 v137, 0xbfb8aa3b, v20
	v_exp_f32_e32 v138, v137
	v_mul_f32_e32 v137, 0xbfb8aa3b, v21
	v_exp_f32_e32 v139, v137
	v_rcp_f32_e32 v137, v133
	v_add_f32_e32 v133, 1.0, v138
	v_rcp_f32_e32 v138, v133
	v_add_f32_e32 v133, 1.0, v139
	v_pk_mul_f32 v[136:137], v[26:27], v[136:137]
	v_rcp_f32_e32 v139, v133
	v_cvt_pk_bf16_f32 v133, v136, v137
	global_store_dwordx4 v[134:135], v[130:133], off sc1
	v_mul_f32_e32 v136, 0xbfb8aa3b, v17
	v_exp_f32_e32 v137, v136
	v_mul_f32_e32 v132, 0xbfb8aa3b, v22
	v_exp_f32_e32 v132, v132
	v_mul_f32_e32 v133, 0xbfb8aa3b, v23
	v_exp_f32_e32 v133, v133
	v_pk_mul_f32 v[130:131], v[20:21], v[138:139]
	s_nop 0
	v_cvt_pk_bf16_f32 v130, v130, v131
	v_add_f32_e32 v131, 1.0, v132
	v_rcp_f32_e32 v132, v131
	v_add_f32_e32 v131, 1.0, v133
	v_rcp_f32_e32 v133, v131
	v_mul_f32_e32 v131, 0xbfb8aa3b, v16
	v_exp_f32_e32 v131, v131
	v_pk_mul_f32 v[132:133], v[22:23], v[132:133]
	v_add_f32_e32 v131, 1.0, v131
	v_rcp_f32_e32 v136, v131
	v_add_f32_e32 v131, 1.0, v137
	v_mul_f32_e32 v137, 0xbfb8aa3b, v18
	v_exp_f32_e32 v138, v137
	v_mul_f32_e32 v137, 0xbfb8aa3b, v19
	v_exp_f32_e32 v139, v137
	v_rcp_f32_e32 v137, v131
	v_add_f32_e32 v131, 1.0, v138
	v_rcp_f32_e32 v138, v131
	v_add_f32_e32 v131, 1.0, v139
	v_rcp_f32_e32 v139, v131
	v_cvt_pk_bf16_f32 v131, v132, v133
	v_pk_mul_f32 v[132:133], v[16:17], v[136:137]
	v_pk_mul_f32 v[136:137], v[18:19], v[138:139]
	v_cvt_pk_bf16_f32 v132, v132, v133
	v_cvt_pk_bf16_f32 v133, v136, v137
	global_store_dwordx4 v[134:135], v[130:133], off offset:256 sc1
	s_nop 1
	v_mul_f32_e32 v132, 0xbfb8aa3b, v12
	v_exp_f32_e32 v134, v132
	v_mul_f32_e32 v132, 0xbfb8aa3b, v13
	v_add_u32_e32 v130, s8, v196
	v_exp_f32_e32 v135, v132
	v_ashrrev_i32_e32 v131, 31, v130
	v_lshlrev_b64 v[130:131], 11, v[130:131]
	v_lshl_add_u64 v[132:133], v[128:129], 0, v[130:131]
	v_mul_f32_e32 v130, 0xbfb8aa3b, v14
	v_mul_f32_e32 v131, 0xbfb8aa3b, v15
	v_add_f32_e32 v128, 1.0, v134
	v_add_f32_e32 v129, 1.0, v135
	v_exp_f32_e32 v130, v130
	v_exp_f32_e32 v131, v131
	v_mul_f32_e32 v134, 0xbfb8aa3b, v8
	v_mul_f32_e32 v135, 0xbfb8aa3b, v9
	v_exp_f32_e32 v134, v134
	v_exp_f32_e32 v135, v135
	v_add_f32_e32 v130, 1.0, v130
	v_add_f32_e32 v131, 1.0, v131
	v_rcp_f32_e32 v128, v128
	v_rcp_f32_e32 v129, v129
	v_rcp_f32_e32 v130, v130
	v_rcp_f32_e32 v131, v131
	v_add_f32_e32 v134, 1.0, v134
	v_add_f32_e32 v135, 1.0, v135
	v_rcp_f32_e32 v134, v134
	v_rcp_f32_e32 v135, v135
	v_pk_mul_f32 v[128:129], v[12:13], v[128:129]
	v_pk_mul_f32 v[130:131], v[14:15], v[130:131]
	v_cvt_pk_bf16_f32 v128, v128, v129
	v_cvt_pk_bf16_f32 v129, v130, v131
	v_pk_mul_f32 v[130:131], v[8:9], v[134:135]
	v_mul_f32_e32 v134, 0xbfb8aa3b, v10
	v_exp_f32_e32 v134, v134
	v_mul_f32_e32 v135, 0xbfb8aa3b, v11
	v_exp_f32_e32 v135, v135
	v_cvt_pk_bf16_f32 v130, v130, v131
	v_add_f32_e32 v131, 1.0, v134
	v_rcp_f32_e32 v134, v131
	v_add_f32_e32 v131, 1.0, v135
	v_mul_f32_e32 v135, 0xbfb8aa3b, v4
	v_exp_f32_e32 v136, v135
	v_mul_f32_e32 v135, 0xbfb8aa3b, v5
	v_exp_f32_e32 v137, v135
	v_rcp_f32_e32 v135, v131
	v_add_f32_e32 v131, 1.0, v136
	v_rcp_f32_e32 v136, v131
	v_add_f32_e32 v131, 1.0, v137
	v_pk_mul_f32 v[134:135], v[10:11], v[134:135]
	v_rcp_f32_e32 v137, v131
	v_cvt_pk_bf16_f32 v131, v134, v135
	global_store_dwordx4 v[132:133], v[128:131], off sc1
	v_mul_f32_e32 v134, 0xbfb8aa3b, v1
	v_exp_f32_e32 v135, v134
	v_mul_f32_e32 v130, 0xbfb8aa3b, v6
	v_exp_f32_e32 v130, v130
	v_mul_f32_e32 v131, 0xbfb8aa3b, v7
	v_exp_f32_e32 v131, v131
	v_pk_mul_f32 v[128:129], v[4:5], v[136:137]
	s_nop 0
	v_cvt_pk_bf16_f32 v128, v128, v129
	v_add_f32_e32 v129, 1.0, v130
	v_rcp_f32_e32 v130, v129
	v_add_f32_e32 v129, 1.0, v131
	v_rcp_f32_e32 v131, v129
	v_mul_f32_e32 v129, 0xbfb8aa3b, v0
	v_exp_f32_e32 v129, v129
	v_pk_mul_f32 v[130:131], v[6:7], v[130:131]
	v_add_f32_e32 v129, 1.0, v129
	v_rcp_f32_e32 v134, v129
	v_add_f32_e32 v129, 1.0, v135
	v_mul_f32_e32 v135, 0xbfb8aa3b, v2
	v_exp_f32_e32 v136, v135
	v_mul_f32_e32 v135, 0xbfb8aa3b, v3
	v_exp_f32_e32 v137, v135
	v_rcp_f32_e32 v135, v129
	v_add_f32_e32 v129, 1.0, v136
	v_rcp_f32_e32 v136, v129
	v_add_f32_e32 v129, 1.0, v137
	v_rcp_f32_e32 v137, v129
	v_cvt_pk_bf16_f32 v129, v130, v131
	v_pk_mul_f32 v[130:131], v[0:1], v[134:135]
	v_pk_mul_f32 v[134:135], v[2:3], v[136:137]
	v_cvt_pk_bf16_f32 v130, v130, v131
	v_cvt_pk_bf16_f32 v131, v134, v135
	global_store_dwordx4 v[132:133], v[128:131], off offset:256 sc1

; __device__ __forceinline__ unsigned cvtpk(float lo, float hi) { f32x2 v = {lo, hi}; bf16x2_t b = __builtin_convertvector(v, bf16x2_t); return __builtin_bit_cast(unsigned, b); }
;     __device__ __forceinline__ void operator()(const f32x4 (&acc)[2][2][4][2], const pg8::Unit& u, int wr, int wc, int fr, int fq) const {
;     ...
;         } else {
;             const int sfq = (fq == 1) ? 2 : ((fq == 2) ? 1 : fq);
;             bf16_t* VT = (bf16_t*)(ws + WS_VT);
; #pragma unroll
;             for (int ai = 0; ai < 2; ++ai)
; #pragma unroll
;                 for (int m = 0; m < 4; ++m) {
;                     const int f = 256 * u.pm + 128 * ai + 64 * wr + 16 * m + fr;
;                     bf16_t* rowp = VT + (size_t)f * NTOK + 256 * u.pn + 32 * wc + 4 * sfq;
; #pragma unroll
;                     for (int bj = 0; bj < 2; ++bj)
; #pragma unroll
;                         for (int n = 0; n < 2; ++n) { const f32x4 v = acc[ai][bj][m][n]; u32x2 w; w.x = cvtpk(v[0], v[1]); w.y = cvtpk(v[2], v[3]); *(u32x2*)(rowp + 128 * bj + 16 * n) = w; }
;                 }
.LBB0_611:
	s_add_u32 s4, s44, 0x6b00000
	s_addc_u32 s5, s45, 0
	s_lshl_b32 s28, s67, 8
	v_add_u32_e32 v130, s28, v169
	v_mov_b64_e32 v[128:129], s[4:5]
	v_mad_i64_i32 v[130:131], s[4:5], v130, s62, v[128:129]
	s_lshl_b32 s4, s68, 8
	s_ashr_i32 s5, s4, 31
	s_lshl_b64 s[4:5], s[4:5], 1
	v_lshl_add_u64 v[130:131], v[130:131], 0, s[4:5]
	s_lshl_b32 s8, s53, 1
	v_lshl_add_u64 v[130:131], v[130:131], 0, s[8:9]
	v_mov_b32_e32 v177, v167
	v_lshl_add_u64 v[130:131], v[130:131], 0, v[176:177]
	v_cvt_pk_bf16_f32 v132, v124, v125
	v_cvt_pk_bf16_f32 v133, v126, v127
	v_cvt_pk_bf16_f32 v134, v120, v121
	v_cvt_pk_bf16_f32 v135, v122, v123
	s_nop 1
	v_permlane32_swap_b32_e32 v132, v134
	v_permlane32_swap_b32_e32 v133, v135
	global_store_dwordx4 v[130:131], v[132:135], off sc1
	v_cvt_pk_bf16_f32 v136, v116, v117
	v_cvt_pk_bf16_f32 v137, v118, v119
	v_cvt_pk_bf16_f32 v138, v112, v113
	v_cvt_pk_bf16_f32 v139, v114, v115
	s_nop 1
	v_permlane32_swap_b32_e32 v136, v138
	v_permlane32_swap_b32_e32 v137, v139
	global_store_dwordx4 v[130:131], v[136:139], off offset:256 sc1
	v_add_u32_e32 v130, s28, v190
	v_mad_i64_i32 v[130:131], s[20:21], v130, s62, v[128:129]
	v_lshl_add_u64 v[130:131], v[130:131], 0, s[4:5]
	v_lshl_add_u64 v[130:131], v[130:131], 0, s[8:9]
	v_lshl_add_u64 v[130:131], v[130:131], 0, v[176:177]
	v_cvt_pk_bf16_f32 v132, v108, v109
	v_cvt_pk_bf16_f32 v133, v110, v111
	v_cvt_pk_bf16_f32 v134, v104, v105
	v_cvt_pk_bf16_f32 v135, v106, v107
	s_nop 1
	v_permlane32_swap_b32_e32 v132, v134
	v_permlane32_swap_b32_e32 v133, v135
	global_store_dwordx4 v[130:131], v[132:135], off sc1
	v_cvt_pk_bf16_f32 v136, v100, v101
	v_cvt_pk_bf16_f32 v137, v102, v103
	v_cvt_pk_bf16_f32 v138, v96, v97
	v_cvt_pk_bf16_f32 v139, v98, v99
	s_nop 1
	v_permlane32_swap_b32_e32 v136, v138
	v_permlane32_swap_b32_e32 v137, v139
	global_store_dwordx4 v[130:131], v[136:139], off offset:256 sc1
	v_add_u32_e32 v130, s28, v191
	v_mad_i64_i32 v[130:131], s[20:21], v130, s62, v[128:129]
	v_lshl_add_u64 v[130:131], v[130:131], 0, s[4:5]
	v_lshl_add_u64 v[130:131], v[130:131], 0, s[8:9]
	v_lshl_add_u64 v[130:131], v[130:131], 0, v[176:177]
	v_cvt_pk_bf16_f32 v132, v92, v93
	v_cvt_pk_bf16_f32 v133, v94, v95
	v_cvt_pk_bf16_f32 v134, v88, v89
	v_cvt_pk_bf16_f32 v135, v90, v91
	s_nop 1
	v_permlane32_swap_b32_e32 v132, v134
	v_permlane32_swap_b32_e32 v133, v135
	global_store_dwordx4 v[130:131], v[132:135], off sc1
	v_cvt_pk_bf16_f32 v136, v84, v85
	v_cvt_pk_bf16_f32 v137, v86, v87
	v_cvt_pk_bf16_f32 v138, v80, v81
	v_cvt_pk_bf16_f32 v139, v82, v83
	s_nop 1
	v_permlane32_swap_b32_e32 v136, v138
	v_permlane32_swap_b32_e32 v137, v139
	global_store_dwordx4 v[130:131], v[136:139], off offset:256 sc1
	v_add_u32_e32 v130, s28, v192
	v_mad_i64_i32 v[130:131], s[20:21], v130, s62, v[128:129]
	v_lshl_add_u64 v[130:131], v[130:131], 0, s[4:5]
	v_lshl_add_u64 v[130:131], v[130:131], 0, s[8:9]
	v_lshl_add_u64 v[130:131], v[130:131], 0, v[176:177]
	v_cvt_pk_bf16_f32 v132, v76, v77
	v_cvt_pk_bf16_f32 v133, v78, v79
	v_cvt_pk_bf16_f32 v134, v72, v73
	v_cvt_pk_bf16_f32 v135, v74, v75
	s_nop 1
	v_permlane32_swap_b32_e32 v132, v134
	v_permlane32_swap_b32_e32 v133, v135
	global_store_dwordx4 v[130:131], v[132:135], off sc1
	v_cvt_pk_bf16_f32 v136, v68, v69
	v_cvt_pk_bf16_f32 v137, v70, v71
	v_cvt_pk_bf16_f32 v138, v64, v65
	v_cvt_pk_bf16_f32 v139, v66, v67
	s_nop 1
	v_permlane32_swap_b32_e32 v136, v138
	v_permlane32_swap_b32_e32 v137, v139
	global_store_dwordx4 v[130:131], v[136:139], off offset:256 sc1
	v_add_u32_e32 v130, s28, v193
	v_mad_i64_i32 v[130:131], s[20:21], v130, s62, v[128:129]
	v_lshl_add_u64 v[130:131], v[130:131], 0, s[4:5]
	v_lshl_add_u64 v[130:131], v[130:131], 0, s[8:9]
	v_lshl_add_u64 v[130:131], v[130:131], 0, v[176:177]
	v_cvt_pk_bf16_f32 v132, v60, v61
	v_cvt_pk_bf16_f32 v133, v62, v63
	v_cvt_pk_bf16_f32 v134, v56, v57
	v_cvt_pk_bf16_f32 v135, v58, v59
	s_nop 1
	v_permlane32_swap_b32_e32 v132, v134
	v_permlane32_swap_b32_e32 v133, v135
	global_store_dwordx4 v[130:131], v[132:135], off sc1
	v_cvt_pk_bf16_f32 v136, v52, v53
	v_cvt_pk_bf16_f32 v137, v54, v55
	v_cvt_pk_bf16_f32 v138, v48, v49
	v_cvt_pk_bf16_f32 v139, v50, v51
	s_nop 1
	v_permlane32_swap_b32_e32 v136, v138
	v_permlane32_swap_b32_e32 v137, v139
	global_store_dwordx4 v[130:131], v[136:139], off offset:256 sc1
	v_add_u32_e32 v130, s28, v194
	v_mad_i64_i32 v[130:131], s[20:21], v130, s62, v[128:129]
	v_lshl_add_u64 v[130:131], v[130:131], 0, s[4:5]
	v_lshl_add_u64 v[130:131], v[130:131], 0, s[8:9]
	v_lshl_add_u64 v[130:131], v[130:131], 0, v[176:177]
	v_cvt_pk_bf16_f32 v132, v44, v45
	v_cvt_pk_bf16_f32 v133, v46, v47
	v_cvt_pk_bf16_f32 v134, v40, v41
	v_cvt_pk_bf16_f32 v135, v42, v43
	s_nop 1
	v_permlane32_swap_b32_e32 v132, v134
	v_permlane32_swap_b32_e32 v133, v135
	global_store_dwordx4 v[130:131], v[132:135], off sc1
	v_cvt_pk_bf16_f32 v136, v36, v37
	v_cvt_pk_bf16_f32 v137, v38, v39
	v_cvt_pk_bf16_f32 v138, v32, v33
	v_cvt_pk_bf16_f32 v139, v34, v35
	s_nop 1
	v_permlane32_swap_b32_e32 v136, v138
	v_permlane32_swap_b32_e32 v137, v139
	global_store_dwordx4 v[130:131], v[136:139], off offset:256 sc1
	v_add_u32_e32 v130, s28, v195
	v_mad_i64_i32 v[130:131], s[20:21], v130, s62, v[128:129]
	v_lshl_add_u64 v[130:131], v[130:131], 0, s[4:5]
	v_lshl_add_u64 v[130:131], v[130:131], 0, s[8:9]
	v_lshl_add_u64 v[130:131], v[130:131], 0, v[176:177]
	v_cvt_pk_bf16_f32 v132, v28, v29
	v_cvt_pk_bf16_f32 v133, v30, v31
	v_cvt_pk_bf16_f32 v134, v24, v25
	v_cvt_pk_bf16_f32 v135, v26, v27
	s_nop 1
	v_permlane32_swap_b32_e32 v132, v134
	v_permlane32_swap_b32_e32 v133, v135
	global_store_dwordx4 v[130:131], v[132:135], off sc1
	v_cvt_pk_bf16_f32 v136, v20, v21
	v_cvt_pk_bf16_f32 v137, v22, v23
	v_cvt_pk_bf16_f32 v138, v16, v17
	v_cvt_pk_bf16_f32 v139, v18, v19
	s_nop 1
	v_permlane32_swap_b32_e32 v136, v138
	v_permlane32_swap_b32_e32 v137, v139
	global_store_dwordx4 v[130:131], v[136:139], off offset:256 sc1
	v_add_u32_e32 v130, s28, v196
	v_mad_i64_i32 v[128:129], s[20:21], v130, s62, v[128:129]
	v_lshl_add_u64 v[128:129], v[128:129], 0, s[4:5]
	v_lshl_add_u64 v[128:129], v[128:129], 0, s[8:9]
	v_lshl_add_u64 v[128:129], v[128:129], 0, v[176:177]
	v_cvt_pk_bf16_f32 v132, v12, v13
	v_cvt_pk_bf16_f32 v133, v14, v15
	v_cvt_pk_bf16_f32 v134, v8, v9
	v_cvt_pk_bf16_f32 v135, v10, v11
	s_nop 1
	v_permlane32_swap_b32_e32 v132, v134
	v_permlane32_swap_b32_e32 v133, v135
	global_store_dwordx4 v[128:129], v[132:135], off sc1
	v_cvt_pk_bf16_f32 v136, v4, v5
	v_cvt_pk_bf16_f32 v137, v6, v7
	v_cvt_pk_bf16_f32 v138, v0, v1
	v_cvt_pk_bf16_f32 v139, v2, v3
	s_nop 1
	v_permlane32_swap_b32_e32 v136, v138
	v_permlane32_swap_b32_e32 v137, v139
	global_store_dwordx4 v[128:129], v[136:139], off offset:256 sc1
	s_cbranch_execnz .LBB0_610

;     __device__ __forceinline__ void operator()(const f32x4 (&acc)[2][2][4][2], const pg8::Unit& u, int wr, int wc, int fr, int fq) const {
;     ...
;             for (int ai = 0; ai < 2; ++ai) {
;                 const int rpos = 4 * u.pm + 2 * ai + wr;
;                 f32x4 cr0, cr1;
;                 if (kind == 0) { const f32x4* tp = (const f32x4*)(tab + rpos * 16 + 4 * fq); cr0 = tp[0]; cr1 = tp[1]; }
;                 else { cr0 = (f32x4){1.f, 0.f, 1.f, 0.f}; cr1 = cr0; }
; #pragma unroll
;                 for (int m = 0; m < 4; ++m) {
;                     const int t = 256 * u.pm + 128 * ai + 64 * wr + 16 * m + fr;
;                     float ss = 0.f;
; #pragma unroll
;                     for (int bj = 0; bj < 2; ++bj)
; #pragma unroll
;                         for (int n = 0; n < 2; ++n) { const f32x4 v = acc[ai][bj][m][n]; ss += (v[0] * v[0] + v[1] * v[1]) + (v[2] * v[2] + v[3] * v[3]); }
;                     ss += __shfl_xor(ss, 16); ss += __shfl_xor(ss, 32);
;                     const float rstd = __builtin_amdgcn_rsqf(ss * (1.0f / 64.0f) + EPS) * osc;
;                     f32x4 cc0, cc1;
;                     if (kind == 0) { const f32x4* tp = (const f32x4*)(tab + (16 * m + fr) * 16 + 4 * fq); cc0 = tp[0]; cc1 = tp[1]; }
;                     else { cc0 = (f32x4){1.f, 0.f, 1.f, 0.f}; cc1 = cc0; }
;                     bf16_t* rowp = dst + (size_t)(rowoff + t) * 1024 + G * 64 + 8 * fq;
; #pragma unroll
;                     for (int bj = 0; bj < 2; ++bj) {
;                         const f32x4 x1 = acc[ai][bj][m][0] * g[bj][0] * rstd, x2 = acc[ai][bj][m][1] * g[bj][1] * rstd;
;                         const f32x4 ca = bj == 0 ? cr0 : cc0, cb = bj == 0 ? cr1 : cc1;
;                         const float co[4] = {ca[0], ca[2], cb[0], cb[2]}, si[4] = {ca[1], ca[3], cb[1], cb[3]};
;                         float o1[4], o2[4];
; #pragma unroll
;                         for (int e = 0; e < 4; ++e) { o1[e] = x1[e] * co[e] - x2[e] * si[e]; o2[e] = x2[e] * co[e] + x1[e] * si[e]; }
;                         u32x4 w; w.x = cvtpk(o1[0], o1[1]); w.y = cvtpk(o1[2], o1[3]); w.z = cvtpk(o2[0], o2[1]); w.w = cvtpk(o2[2], o2[3]);
;                         *(u32x4*)(rowp + 32 * bj) = w;
;                     }
.LBB0_621:
	s_lshl_b32 s69, s67, 8
	s_add_u32 s44, s44, s46
	s_addc_u32 s45, s45, s47
	s_xor_b64 s[20:21], s[20:21], s[28:29]
	s_and_b64 s[20:21], s[20:21], exec
	s_waitcnt lgkmcnt(0)
	v_add_f32_e32 v138, v138, v139
	s_cselect_b32 s20, 0x100, 0
	s_lshl_b32 s21, s68, 2
	v_fmamk_f32 v138, v138, 0x3c800000, v199
	s_and_b32 s21, s21, 12
	v_rsq_f32_e32 v138, v138
	s_or_b32 s21, s21, s52
	v_add_u32_e32 v202, s20, v169
	s_lshl_b32 s20, s21, 7
	s_add_u32 s20, s44, s20
	v_add_u32_e32 v146, s69, v202
	s_addc_u32 s21, s45, 0
	v_lshlrev_b32_e32 v166, 1, v164
	v_ashrrev_i32_e32 v147, 31, v146
	v_mul_f32_e32 v204, s8, v138
	v_lshl_add_u64 v[138:139], s[20:21], 0, v[166:167]
	v_lshlrev_b64 v[142:143], 11, v[146:147]
	v_lshl_add_u64 v[206:207], v[138:139], 0, v[142:143]
	v_mov_b32_e32 v159, v121
	s_waitcnt vmcnt(0)
	v_mov_b32_e32 v143, v133
	v_mov_b32_e32 v121, v125
	v_mov_b32_e32 v133, v153
	v_mov_b32_e32 v158, v124
	v_mov_b32_e32 v142, v152
	v_pk_mul_f32 v[120:121], v[120:121], v[132:133]
	v_pk_mul_f32 v[158:159], v[158:159], v[142:143]
	v_pk_mul_f32 v[120:121], v[120:121], v[204:205] op_sel_hi:[1,0]
	v_pk_mul_f32 v[184:185], v[158:159], v[204:205] op_sel_hi:[1,0]
	v_pk_mul_f32 v[124:125], v[140:141], v[120:121]
	v_mov_b32_e32 v158, v182
	v_pk_fma_f32 v[208:209], v[182:183], v[184:185], v[124:125]
	v_mov_b32_e32 v125, v121
	v_mov_b32_e32 v159, v141
	v_mov_b32_e32 v121, v185
	v_mov_b32_e32 v152, v140
	v_mov_b32_e32 v153, v183
	v_mov_b32_e32 v124, v184
	v_pk_mul_f32 v[120:121], v[158:159], v[120:121]
	v_mov_b32_e32 v184, v126
	v_pk_fma_f32 v[120:121], v[152:153], v[124:125], v[120:121] neg_lo:[0,0,1] neg_hi:[0,0,1]
	v_mov_b32_e32 v185, v123
	v_mov_b32_e32 v124, v154
	v_mov_b32_e32 v125, v135
	v_mov_b32_e32 v123, v127
	v_mov_b32_e32 v135, v155
	v_pk_mul_f32 v[184:185], v[184:185], v[124:125]
	v_pk_mul_f32 v[122:123], v[122:123], v[134:135]
	v_pk_mul_f32 v[210:211], v[184:185], v[204:205] op_sel_hi:[1,0]
	v_pk_mul_f32 v[122:123], v[122:123], v[204:205] op_sel_hi:[1,0]
	v_mov_b32_e32 v184, v180
	v_pk_mul_f32 v[126:127], v[136:137], v[122:123]
	v_mov_b32_e32 v213, v123
	v_mov_b32_e32 v185, v137
	v_mov_b32_e32 v123, v211
	v_mov_b32_e32 v154, v136
	v_mov_b32_e32 v155, v181
	v_mov_b32_e32 v212, v210
	v_pk_mul_f32 v[122:123], v[184:185], v[122:123]
	v_pk_fma_f32 v[126:127], v[180:181], v[210:211], v[126:127]
	v_pk_fma_f32 v[122:123], v[154:155], v[212:213], v[122:123] neg_lo:[0,0,1] neg_hi:[0,0,1]
	v_cvt_pk_bf16_f32 v120, v120, v121
	v_cvt_pk_bf16_f32 v121, v122, v123
	v_cvt_pk_bf16_f32 v122, v208, v209
	v_cvt_pk_bf16_f32 v123, v126, v127
	global_store_dwordx4 v[206:207], v[120:123], off sc1
	s_and_b64 vcc, exec, s[4:5]
	s_nop 0
	v_mov_b32_e32 v121, v113
	v_mov_b32_e32 v123, v129
	v_mov_b32_e32 v113, v117
	v_mov_b32_e32 v129, v149
	v_mov_b32_e32 v120, v116
	v_mov_b32_e32 v122, v148
	v_pk_mul_f32 v[112:113], v[112:113], v[128:129]
	v_pk_mul_f32 v[120:121], v[120:121], v[122:123]
	v_pk_mul_f32 v[112:113], v[112:113], v[204:205] op_sel_hi:[1,0]
	v_pk_mul_f32 v[120:121], v[120:121], v[204:205] op_sel_hi:[1,0]
	v_pk_mul_f32 v[116:117], v[112:113], v[156:157]
	v_mov_b32_e32 v127, v113
	v_pk_fma_f32 v[116:117], v[120:121], v[188:189], v[116:117]
	v_mov_b32_e32 v149, v189
	v_mov_b32_e32 v113, v121
	v_mov_b32_e32 v189, v157
	v_mov_b32_e32 v126, v120
	v_mov_b32_e32 v148, v156
	v_pk_mul_f32 v[112:113], v[112:113], v[188:189]
	v_mov_b32_e32 v121, v115
	v_pk_fma_f32 v[112:113], v[126:127], v[148:149], v[112:113] neg_lo:[0,0,1] neg_hi:[0,0,1]
	v_mov_b32_e32 v127, v131
	v_mov_b32_e32 v115, v119
	v_mov_b32_e32 v131, v151
	v_mov_b32_e32 v120, v118
	v_mov_b32_e32 v126, v150
	v_pk_mul_f32 v[114:115], v[114:115], v[130:131]
	v_pk_mul_f32 v[120:121], v[120:121], v[126:127]
	v_pk_mul_f32 v[114:115], v[114:115], v[204:205] op_sel_hi:[1,0]
	v_pk_mul_f32 v[120:121], v[120:121], v[204:205] op_sel_hi:[1,0]
	v_pk_mul_f32 v[118:119], v[114:115], v[144:145]
	v_mov_b32_e32 v148, v120
	v_pk_fma_f32 v[118:119], v[120:121], v[186:187], v[118:119]
	v_cvt_pk_bf16_f32 v112, v112, v113
	v_mul_f32_e32 v113, v109, v109
	v_mul_f32_e32 v120, v111, v111
	v_fmac_f32_e32 v113, v108, v108
	v_fmac_f32_e32 v120, v110, v110
	v_mov_b32_e32 v149, v115
	v_mov_b32_e32 v115, v121
	v_add_f32_e32 v113, v113, v120
	v_mul_f32_e32 v120, v105, v105
	v_mul_f32_e32 v121, v107, v107
	v_fmac_f32_e32 v120, v104, v104
	v_fmac_f32_e32 v121, v106, v106
	v_add_f32_e32 v120, v120, v121
	v_add_f32_e32 v113, v113, v120
	v_mul_f32_e32 v120, v101, v101
	v_mul_f32_e32 v121, v103, v103
	v_fmac_f32_e32 v120, v100, v100
	v_fmac_f32_e32 v121, v102, v102
	v_add_f32_e32 v120, v120, v121
	v_add_f32_e32 v113, v113, v120
	v_mul_f32_e32 v120, v97, v97
	v_mul_f32_e32 v121, v99, v99
	v_fmac_f32_e32 v120, v96, v96
	v_fmac_f32_e32 v121, v98, v98
	v_add_f32_e32 v120, v120, v121
	v_add_f32_e32 v120, v113, v120
	ds_bpermute_b32 v121, v177, v120
	v_mov_b32_e32 v151, v187
	v_mov_b32_e32 v187, v145
	v_mov_b32_e32 v150, v144
	v_pk_mul_f32 v[114:115], v[114:115], v[186:187]
	v_mov_b32_e32 v144, 0
	v_pk_fma_f32 v[114:115], v[148:149], v[150:151], v[114:115] neg_lo:[0,0,1] neg_hi:[0,0,1]
	v_mov_b32_e32 v148, 0
	v_cvt_pk_bf16_f32 v113, v114, v115
	v_cvt_pk_bf16_f32 v114, v116, v117
	v_cvt_pk_bf16_f32 v115, v118, v119
	global_store_dwordx4 v[206:207], v[112:115], off offset:64 sc1
	v_mov_b32_e32 v149, 1.0
	v_mov_b32_e32 v118, 1.0
	s_waitcnt lgkmcnt(0)
	v_add_f32_e32 v113, v120, v121
	ds_bpermute_b32 v145, v201, v113
	v_mov_b32_e32 v112, 1.0
	v_mov_b32_e32 v114, 1.0
	v_mov_b32_e32 v115, 0
	v_mov_b32_e32 v116, 0
	v_mov_b32_e32 v117, 1.0
	v_mov_b32_e32 v119, 0
	s_cbranch_vccnz .LBB0_623
	v_lshlrev_b32_e32 v166, 3, v170
	v_lshl_add_u64 v[118:119], v[178:179], 0, v[166:167]
	global_load_dwordx4 v[114:117], v[118:119], off offset:2064
	s_nop 0
	global_load_dwordx4 v[118:121], v[118:119], off offset:2048
	s_waitcnt vmcnt(1)
	v_mov_b32_e32 v148, v115
	v_mov_b32_e32 v149, v116
	v_mov_b32_e32 v115, v117
	s_waitcnt vmcnt(0)
	v_mov_b32_e32 v116, v119
	v_mov_b32_e32 v117, v120
	v_mov_b32_e32 v119, v121
;     __device__ __forceinline__ void operator()(const f32x4 (&acc)[2][2][4][2], const pg8::Unit& u, int wr, int wc, int fr, int fq) const {
;     ...
;             for (int ai = 0; ai < 2; ++ai) {
;                 const int rpos = 4 * u.pm + 2 * ai + wr;
;                 f32x4 cr0, cr1;
;                 if (kind == 0) { const f32x4* tp = (const f32x4*)(tab + rpos * 16 + 4 * fq); cr0 = tp[0]; cr1 = tp[1]; }
;                 else { cr0 = (f32x4){1.f, 0.f, 1.f, 0.f}; cr1 = cr0; }
; #pragma unroll
;                 for (int m = 0; m < 4; ++m) {
;                     const int t = 256 * u.pm + 128 * ai + 64 * wr + 16 * m + fr;
;                     float ss = 0.f;
; #pragma unroll
;                     for (int bj = 0; bj < 2; ++bj)
; #pragma unroll
;                         for (int n = 0; n < 2; ++n) { const f32x4 v = acc[ai][bj][m][n]; ss += (v[0] * v[0] + v[1] * v[1]) + (v[2] * v[2] + v[3] * v[3]); }
;                     ss += __shfl_xor(ss, 16); ss += __shfl_xor(ss, 32);
;                     const float rstd = __builtin_amdgcn_rsqf(ss * (1.0f / 64.0f) + EPS) * osc;
;                     f32x4 cc0, cc1;
;                     if (kind == 0) { const f32x4* tp = (const f32x4*)(tab + (16 * m + fr) * 16 + 4 * fq); cc0 = tp[0]; cc1 = tp[1]; }
;                     else { cc0 = (f32x4){1.f, 0.f, 1.f, 0.f}; cc1 = cc0; }
;                     bf16_t* rowp = dst + (size_t)(rowoff + t) * 1024 + G * 64 + 8 * fq;
; #pragma unroll
;                     for (int bj = 0; bj < 2; ++bj) {
;                         const f32x4 x1 = acc[ai][bj][m][0] * g[bj][0] * rstd, x2 = acc[ai][bj][m][1] * g[bj][1] * rstd;
;                         const f32x4 ca = bj == 0 ? cr0 : cc0, cb = bj == 0 ? cr1 : cc1;
;                         const float co[4] = {ca[0], ca[2], cb[0], cb[2]}, si[4] = {ca[1], ca[3], cb[1], cb[3]};
;                         float o1[4], o2[4];
; #pragma unroll
;                         for (int e = 0; e < 4; ++e) { o1[e] = x1[e] * co[e] - x2[e] * si[e]; o2[e] = x2[e] * co[e] + x1[e] * si[e]; }
;                         u32x4 w; w.x = cvtpk(o1[0], o1[1]); w.y = cvtpk(o1[2], o1[3]); w.z = cvtpk(o2[0], o2[1]); w.w = cvtpk(o2[2], o2[3]);
;                         *(u32x4*)(rowp + 32 * bj) = w;
;                     }
.LBB0_623:
	s_waitcnt lgkmcnt(0)
	v_add_f32_e32 v113, v113, v145
	v_fmamk_f32 v113, v113, 0x3c800000, v199
	v_rsq_f32_e32 v113, v113
	v_mov_b32_e32 v157, v105
	v_mov_b32_e32 v105, v109
	v_mov_b32_e32 v156, v108
	v_mul_f32_e32 v150, s8, v113
	v_pk_mul_f32 v[104:105], v[104:105], v[132:133]
	v_pk_mul_f32 v[156:157], v[156:157], v[142:143]
	v_pk_mul_f32 v[104:105], v[104:105], v[150:151] op_sel_hi:[1,0]
	v_pk_mul_f32 v[108:109], v[156:157], v[150:151] op_sel_hi:[1,0]
	v_pk_mul_f32 v[156:157], v[140:141], v[104:105]
	v_mov_b32_e32 v186, v108
	v_pk_fma_f32 v[156:157], v[182:183], v[108:109], v[156:157]
	v_mov_b32_e32 v187, v105
	v_mov_b32_e32 v105, v109
	v_mov_b32_e32 v108, v110
	v_mov_b32_e32 v109, v107
	v_mov_b32_e32 v107, v111
	v_pk_mul_f32 v[108:109], v[108:109], v[124:125]
	v_pk_mul_f32 v[106:107], v[106:107], v[134:135]
	v_pk_mul_f32 v[104:105], v[158:159], v[104:105]
	v_pk_mul_f32 v[108:109], v[108:109], v[150:151] op_sel_hi:[1,0]
	v_pk_mul_f32 v[106:107], v[106:107], v[150:151] op_sel_hi:[1,0]
	v_add3_u32 v120, v202, s69, 16
	v_pk_fma_f32 v[104:105], v[152:153], v[186:187], v[104:105] neg_lo:[0,0,1] neg_hi:[0,0,1]
	v_pk_mul_f32 v[110:111], v[136:137], v[106:107]
	v_mov_b32_e32 v187, v107
	v_mov_b32_e32 v107, v109
	v_ashrrev_i32_e32 v121, 31, v120
	v_mov_b32_e32 v186, v108
	v_pk_mul_f32 v[106:107], v[184:185], v[106:107]
	v_lshlrev_b64 v[120:121], 11, v[120:121]
	v_pk_fma_f32 v[110:111], v[180:181], v[108:109], v[110:111]
	v_pk_fma_f32 v[106:107], v[154:155], v[186:187], v[106:107] neg_lo:[0,0,1] neg_hi:[0,0,1]
	v_lshl_add_u64 v[120:121], v[138:139], 0, v[120:121]
	v_cvt_pk_bf16_f32 v104, v104, v105
	v_cvt_pk_bf16_f32 v105, v106, v107
	v_cvt_pk_bf16_f32 v106, v156, v157
	v_cvt_pk_bf16_f32 v107, v110, v111
	global_store_dwordx4 v[120:121], v[104:107], off sc1
	v_mov_b32_e32 v109, v117
	v_mov_b32_e32 v108, v118
	v_mov_b32_e32 v105, v97
	v_mov_b32_e32 v97, v101
	v_mov_b32_e32 v104, v100
	v_pk_mul_f32 v[96:97], v[96:97], v[128:129]
	v_pk_mul_f32 v[104:105], v[104:105], v[122:123]
	v_pk_mul_f32 v[96:97], v[96:97], v[150:151] op_sel_hi:[1,0]
	v_pk_mul_f32 v[100:101], v[104:105], v[150:151] op_sel_hi:[1,0]
	v_pk_mul_f32 v[104:105], v[96:97], v[118:119]
	v_mov_b32_e32 v107, v97
	v_pk_fma_f32 v[104:105], v[100:101], v[116:117], v[104:105]
	v_mov_b32_e32 v97, v101
	v_mov_b32_e32 v101, v99
	v_mov_b32_e32 v99, v103
	v_mov_b32_e32 v106, v100
	v_mov_b32_e32 v117, v119
	v_mov_b32_e32 v100, v102
	v_pk_mul_f32 v[98:99], v[98:99], v[130:131]
	v_pk_mul_f32 v[96:97], v[96:97], v[116:117]
	v_pk_mul_f32 v[100:101], v[100:101], v[126:127]
	v_pk_mul_f32 v[98:99], v[98:99], v[150:151] op_sel_hi:[1,0]
	v_pk_fma_f32 v[96:97], v[106:107], v[108:109], v[96:97] neg_lo:[0,0,1] neg_hi:[0,0,1]
	v_pk_mul_f32 v[100:101], v[100:101], v[150:151] op_sel_hi:[1,0]
	v_pk_mul_f32 v[102:103], v[98:99], v[114:115]
	v_mov_b32_e32 v106, v100
	v_pk_fma_f32 v[102:103], v[100:101], v[148:149], v[102:103]
	v_cvt_pk_bf16_f32 v96, v96, v97
	v_mul_f32_e32 v97, v93, v93
	v_mul_f32_e32 v100, v95, v95
	v_fmac_f32_e32 v97, v92, v92
	v_fmac_f32_e32 v100, v94, v94
	v_mov_b32_e32 v107, v99
	v_mov_b32_e32 v99, v101
	v_add_f32_e32 v97, v97, v100
	v_mul_f32_e32 v100, v89, v89
	v_mul_f32_e32 v101, v91, v91
	v_fmac_f32_e32 v100, v88, v88
	v_fmac_f32_e32 v101, v90, v90
	v_add_f32_e32 v100, v100, v101
	v_add_f32_e32 v97, v97, v100
	v_mul_f32_e32 v100, v85, v85
	v_mul_f32_e32 v101, v87, v87
	v_fmac_f32_e32 v100, v84, v84
	v_fmac_f32_e32 v101, v86, v86
	v_add_f32_e32 v100, v100, v101
	v_add_f32_e32 v97, v97, v100
	v_mul_f32_e32 v100, v81, v81
	v_mul_f32_e32 v101, v83, v83
	v_fmac_f32_e32 v100, v80, v80
	v_fmac_f32_e32 v101, v82, v82
	v_add_f32_e32 v100, v100, v101
	v_add_f32_e32 v100, v97, v100
	ds_bpermute_b32 v101, v177, v100
	v_mov_b32_e32 v109, v149
	v_mov_b32_e32 v149, v115
	v_mov_b32_e32 v108, v114
	v_pk_mul_f32 v[98:99], v[98:99], v[148:149]
	s_and_b64 vcc, exec, s[4:5]
	v_pk_fma_f32 v[98:99], v[106:107], v[108:109], v[98:99] neg_lo:[0,0,1] neg_hi:[0,0,1]
	v_mov_b32_e32 v145, 1.0
	v_cvt_pk_bf16_f32 v97, v98, v99
	v_cvt_pk_bf16_f32 v99, v102, v103
	s_waitcnt lgkmcnt(0)
	v_add_f32_e32 v102, v100, v101
	ds_bpermute_b32 v103, v201, v102
	v_cvt_pk_bf16_f32 v98, v104, v105
	global_store_dwordx4 v[120:121], v[96:99], off offset:64 sc1
	v_mov_b32_e32 v113, 0
	v_mov_b32_e32 v100, 0
	v_mov_b32_e32 v96, 1.0
	v_mov_b32_e32 v101, 1.0
	v_mov_b32_e32 v97, 0
	s_cbranch_vccnz .LBB0_625
	v_lshlrev_b32_e32 v166, 3, v170
	v_lshl_add_u64 v[96:97], v[178:179], 0, v[166:167]
	v_lshl_add_u64 v[98:99], v[96:97], 0, s[34:35]
	v_add_co_u32_e32 v96, vcc, 0x1000, v96
	global_load_dwordx4 v[112:115], v[98:99], off offset:16
	s_nop 0
	v_addc_co_u32_e32 v97, vcc, 0, v97, vcc
	global_load_dwordx4 v[96:99], v[96:97], off
	s_waitcnt vmcnt(1)
	v_mov_b32_e32 v144, v113
	v_mov_b32_e32 v145, v114
	v_mov_b32_e32 v113, v115
	s_waitcnt vmcnt(0)
	v_mov_b32_e32 v100, v97
	v_mov_b32_e32 v101, v98
	v_mov_b32_e32 v97, v99
;     __device__ __forceinline__ void operator()(const f32x4 (&acc)[2][2][4][2], const pg8::Unit& u, int wr, int wc, int fr, int fq) const {
;     ...
;             for (int ai = 0; ai < 2; ++ai) {
;                 const int rpos = 4 * u.pm + 2 * ai + wr;
;                 f32x4 cr0, cr1;
;                 if (kind == 0) { const f32x4* tp = (const f32x4*)(tab + rpos * 16 + 4 * fq); cr0 = tp[0]; cr1 = tp[1]; }
;                 else { cr0 = (f32x4){1.f, 0.f, 1.f, 0.f}; cr1 = cr0; }
; #pragma unroll
;                 for (int m = 0; m < 4; ++m) {
;                     const int t = 256 * u.pm + 128 * ai + 64 * wr + 16 * m + fr;
;                     float ss = 0.f;
; #pragma unroll
;                     for (int bj = 0; bj < 2; ++bj)
; #pragma unroll
;                         for (int n = 0; n < 2; ++n) { const f32x4 v = acc[ai][bj][m][n]; ss += (v[0] * v[0] + v[1] * v[1]) + (v[2] * v[2] + v[3] * v[3]); }
;                     ss += __shfl_xor(ss, 16); ss += __shfl_xor(ss, 32);
;                     const float rstd = __builtin_amdgcn_rsqf(ss * (1.0f / 64.0f) + EPS) * osc;
;                     f32x4 cc0, cc1;
;                     if (kind == 0) { const f32x4* tp = (const f32x4*)(tab + (16 * m + fr) * 16 + 4 * fq); cc0 = tp[0]; cc1 = tp[1]; }
;                     else { cc0 = (f32x4){1.f, 0.f, 1.f, 0.f}; cc1 = cc0; }
;                     bf16_t* rowp = dst + (size_t)(rowoff + t) * 1024 + G * 64 + 8 * fq;
; #pragma unroll
;                     for (int bj = 0; bj < 2; ++bj) {
;                         const f32x4 x1 = acc[ai][bj][m][0] * g[bj][0] * rstd, x2 = acc[ai][bj][m][1] * g[bj][1] * rstd;
;                         const f32x4 ca = bj == 0 ? cr0 : cc0, cb = bj == 0 ? cr1 : cc1;
;                         const float co[4] = {ca[0], ca[2], cb[0], cb[2]}, si[4] = {ca[1], ca[3], cb[1], cb[3]};
;                         float o1[4], o2[4];
; #pragma unroll
;                         for (int e = 0; e < 4; ++e) { o1[e] = x1[e] * co[e] - x2[e] * si[e]; o2[e] = x2[e] * co[e] + x1[e] * si[e]; }
;                         u32x4 w; w.x = cvtpk(o1[0], o1[1]); w.y = cvtpk(o1[2], o1[3]); w.z = cvtpk(o2[0], o2[1]); w.w = cvtpk(o2[2], o2[3]);
;                         *(u32x4*)(rowp + 32 * bj) = w;
;                     }
.LBB0_625:
	s_waitcnt lgkmcnt(0)
	v_add_f32_e32 v98, v102, v103
	v_fmamk_f32 v98, v98, 0x3c800000, v199
	v_rsq_f32_e32 v102, v98
	v_mov_b32_e32 v105, v89
	v_mov_b32_e32 v89, v93
	v_mov_b32_e32 v104, v92
	v_mul_f32_e32 v102, s8, v102
	v_pk_mul_f32 v[88:89], v[88:89], v[132:133]
	v_pk_mul_f32 v[104:105], v[104:105], v[142:143]
	v_pk_mul_f32 v[88:89], v[88:89], v[102:103] op_sel_hi:[1,0]
	v_pk_mul_f32 v[92:93], v[104:105], v[102:103] op_sel_hi:[1,0]
	v_pk_mul_f32 v[104:105], v[140:141], v[88:89]
	v_mov_b32_e32 v106, v92
	v_pk_fma_f32 v[104:105], v[182:183], v[92:93], v[104:105]
	v_mov_b32_e32 v107, v89
	v_mov_b32_e32 v89, v93
	v_mov_b32_e32 v92, v94
	v_mov_b32_e32 v93, v91
	v_mov_b32_e32 v91, v95
	v_pk_mul_f32 v[92:93], v[92:93], v[124:125]
	v_pk_mul_f32 v[90:91], v[90:91], v[134:135]
	v_pk_mul_f32 v[88:89], v[158:159], v[88:89]
	v_pk_mul_f32 v[92:93], v[92:93], v[102:103] op_sel_hi:[1,0]
	v_pk_mul_f32 v[90:91], v[90:91], v[102:103] op_sel_hi:[1,0]
	v_add3_u32 v98, v202, s69, 32
	v_pk_fma_f32 v[88:89], v[152:153], v[106:107], v[88:89] neg_lo:[0,0,1] neg_hi:[0,0,1]
	v_pk_mul_f32 v[94:95], v[136:137], v[90:91]
	v_mov_b32_e32 v107, v91
	v_mov_b32_e32 v91, v93
	v_ashrrev_i32_e32 v99, 31, v98
	v_mov_b32_e32 v106, v92
	v_pk_mul_f32 v[90:91], v[184:185], v[90:91]
	v_lshlrev_b64 v[98:99], 11, v[98:99]
	v_pk_fma_f32 v[94:95], v[180:181], v[92:93], v[94:95]
	v_pk_fma_f32 v[90:91], v[154:155], v[106:107], v[90:91] neg_lo:[0,0,1] neg_hi:[0,0,1]
	v_lshl_add_u64 v[98:99], v[138:139], 0, v[98:99]
	v_cvt_pk_bf16_f32 v88, v88, v89
	v_cvt_pk_bf16_f32 v89, v90, v91
	v_cvt_pk_bf16_f32 v90, v104, v105
	v_cvt_pk_bf16_f32 v91, v94, v95
	global_store_dwordx4 v[98:99], v[88:91], off sc1
	v_mov_b32_e32 v93, v101
	v_mov_b32_e32 v92, v96
	v_mov_b32_e32 v89, v81
	v_mov_b32_e32 v81, v85
	v_mov_b32_e32 v88, v84
	v_pk_mul_f32 v[80:81], v[80:81], v[128:129]
	v_pk_mul_f32 v[88:89], v[88:89], v[122:123]
	v_pk_mul_f32 v[80:81], v[80:81], v[102:103] op_sel_hi:[1,0]
	v_pk_mul_f32 v[84:85], v[88:89], v[102:103] op_sel_hi:[1,0]
	v_pk_mul_f32 v[88:89], v[80:81], v[96:97]
	v_mov_b32_e32 v91, v81
	v_pk_fma_f32 v[88:89], v[84:85], v[100:101], v[88:89]
	v_mov_b32_e32 v81, v85
	v_mov_b32_e32 v85, v83
	v_mov_b32_e32 v83, v87
	v_mov_b32_e32 v90, v84
	v_mov_b32_e32 v101, v97
	v_mov_b32_e32 v84, v86
	v_pk_mul_f32 v[82:83], v[82:83], v[130:131]
	v_pk_mul_f32 v[80:81], v[80:81], v[100:101]
	v_pk_mul_f32 v[84:85], v[84:85], v[126:127]
	v_pk_mul_f32 v[82:83], v[82:83], v[102:103] op_sel_hi:[1,0]
	v_pk_fma_f32 v[80:81], v[90:91], v[92:93], v[80:81] neg_lo:[0,0,1] neg_hi:[0,0,1]
	v_pk_mul_f32 v[84:85], v[84:85], v[102:103] op_sel_hi:[1,0]
	v_pk_mul_f32 v[86:87], v[82:83], v[112:113]
	v_mov_b32_e32 v90, v84
	v_pk_fma_f32 v[86:87], v[84:85], v[144:145], v[86:87]
	v_cvt_pk_bf16_f32 v80, v80, v81
	v_mul_f32_e32 v81, v77, v77
	v_mul_f32_e32 v84, v79, v79
	v_fmac_f32_e32 v81, v76, v76
	v_fmac_f32_e32 v84, v78, v78
	v_mov_b32_e32 v91, v83
	v_mov_b32_e32 v83, v85
	v_add_f32_e32 v81, v81, v84
	v_mul_f32_e32 v84, v73, v73
	v_mul_f32_e32 v85, v75, v75
	v_fmac_f32_e32 v84, v72, v72
	v_fmac_f32_e32 v85, v74, v74
	v_add_f32_e32 v84, v84, v85
	v_add_f32_e32 v81, v81, v84
	v_mul_f32_e32 v84, v69, v69
	v_mul_f32_e32 v85, v71, v71
	v_fmac_f32_e32 v84, v68, v68
	v_fmac_f32_e32 v85, v70, v70
	v_add_f32_e32 v84, v84, v85
	v_add_f32_e32 v81, v81, v84
	v_mul_f32_e32 v84, v65, v65
	v_mul_f32_e32 v85, v67, v67
	v_fmac_f32_e32 v84, v64, v64
	v_fmac_f32_e32 v85, v66, v66
	v_add_f32_e32 v84, v84, v85
	v_add_f32_e32 v84, v81, v84
	ds_bpermute_b32 v85, v177, v84
	v_mov_b32_e32 v93, v145
	v_mov_b32_e32 v145, v113
	v_mov_b32_e32 v92, v112
	v_pk_mul_f32 v[82:83], v[82:83], v[144:145]
	s_and_b64 vcc, exec, s[4:5]
	v_pk_fma_f32 v[82:83], v[90:91], v[92:93], v[82:83] neg_lo:[0,0,1] neg_hi:[0,0,1]
	v_mov_b32_e32 v90, 0
	v_cvt_pk_bf16_f32 v81, v82, v83
	v_cvt_pk_bf16_f32 v82, v88, v89
	v_cvt_pk_bf16_f32 v83, v86, v87
	global_store_dwordx4 v[98:99], v[80:83], off offset:64 sc1
	v_mov_b32_e32 v92, 0
	v_mov_b32_e32 v93, 1.0
	s_waitcnt lgkmcnt(0)
	v_add_f32_e32 v81, v84, v85
	ds_bpermute_b32 v91, v201, v81
	v_mov_b32_e32 v80, 1.0
	v_mov_b32_e32 v82, 1.0
	v_mov_b32_e32 v83, 0
	v_mov_b32_e32 v86, 1.0
	v_mov_b32_e32 v84, 0
	v_mov_b32_e32 v85, 1.0
	v_mov_b32_e32 v87, 0
	s_cbranch_vccnz .LBB0_627
	v_lshlrev_b32_e32 v166, 3, v170
	v_lshl_add_u64 v[86:87], v[178:179], 0, v[166:167]
	v_lshl_add_u64 v[82:83], v[86:87], 0, s[36:37]
	v_add_co_u32_e32 v86, vcc, 0x1000, v86
	global_load_dwordx4 v[82:85], v[82:83], off offset:16
	s_nop 0
	v_addc_co_u32_e32 v87, vcc, 0, v87, vcc
	global_load_dwordx4 v[86:89], v[86:87], off offset:2048
	s_waitcnt vmcnt(1)
	v_mov_b32_e32 v92, v83
	v_mov_b32_e32 v93, v84
	v_mov_b32_e32 v83, v85
	s_waitcnt vmcnt(0)
	v_mov_b32_e32 v84, v87
	v_mov_b32_e32 v85, v88
	v_mov_b32_e32 v87, v89
;     __device__ __forceinline__ void operator()(const f32x4 (&acc)[2][2][4][2], const pg8::Unit& u, int wr, int wc, int fr, int fq) const {
;     ...
;             for (int ai = 0; ai < 2; ++ai) {
;                 const int rpos = 4 * u.pm + 2 * ai + wr;
;                 f32x4 cr0, cr1;
;                 if (kind == 0) { const f32x4* tp = (const f32x4*)(tab + rpos * 16 + 4 * fq); cr0 = tp[0]; cr1 = tp[1]; }
;                 else { cr0 = (f32x4){1.f, 0.f, 1.f, 0.f}; cr1 = cr0; }
; #pragma unroll
;                 for (int m = 0; m < 4; ++m) {
;                     const int t = 256 * u.pm + 128 * ai + 64 * wr + 16 * m + fr;
;                     float ss = 0.f;
; #pragma unroll
;                     for (int bj = 0; bj < 2; ++bj)
; #pragma unroll
;                         for (int n = 0; n < 2; ++n) { const f32x4 v = acc[ai][bj][m][n]; ss += (v[0] * v[0] + v[1] * v[1]) + (v[2] * v[2] + v[3] * v[3]); }
;                     ss += __shfl_xor(ss, 16); ss += __shfl_xor(ss, 32);
;                     const float rstd = __builtin_amdgcn_rsqf(ss * (1.0f / 64.0f) + EPS) * osc;
;                     f32x4 cc0, cc1;
;                     if (kind == 0) { const f32x4* tp = (const f32x4*)(tab + (16 * m + fr) * 16 + 4 * fq); cc0 = tp[0]; cc1 = tp[1]; }
;                     else { cc0 = (f32x4){1.f, 0.f, 1.f, 0.f}; cc1 = cc0; }
;                     bf16_t* rowp = dst + (size_t)(rowoff + t) * 1024 + G * 64 + 8 * fq;
; #pragma unroll
;                     for (int bj = 0; bj < 2; ++bj) {
;                         const f32x4 x1 = acc[ai][bj][m][0] * g[bj][0] * rstd, x2 = acc[ai][bj][m][1] * g[bj][1] * rstd;
;                         const f32x4 ca = bj == 0 ? cr0 : cc0, cb = bj == 0 ? cr1 : cc1;
;                         const float co[4] = {ca[0], ca[2], cb[0], cb[2]}, si[4] = {ca[1], ca[3], cb[1], cb[3]};
;                         float o1[4], o2[4];
; #pragma unroll
;                         for (int e = 0; e < 4; ++e) { o1[e] = x1[e] * co[e] - x2[e] * si[e]; o2[e] = x2[e] * co[e] + x1[e] * si[e]; }
;                         u32x4 w; w.x = cvtpk(o1[0], o1[1]); w.y = cvtpk(o1[2], o1[3]); w.z = cvtpk(o2[0], o2[1]); w.w = cvtpk(o2[2], o2[3]);
;                         *(u32x4*)(rowp + 32 * bj) = w;
;                     }
.LBB0_627:
	s_waitcnt lgkmcnt(0)
	v_add_f32_e32 v81, v81, v91
	v_fmamk_f32 v81, v81, 0x3c800000, v199
	v_rsq_f32_e32 v81, v81
	v_mov_b32_e32 v97, v73
	v_mov_b32_e32 v73, v77
	v_mov_b32_e32 v96, v76
	v_mul_f32_e32 v94, s8, v81
	v_pk_mul_f32 v[72:73], v[72:73], v[132:133]
	v_pk_mul_f32 v[96:97], v[96:97], v[142:143]
	v_pk_mul_f32 v[72:73], v[72:73], v[94:95] op_sel_hi:[1,0]
	v_pk_mul_f32 v[76:77], v[96:97], v[94:95] op_sel_hi:[1,0]
	v_pk_mul_f32 v[96:97], v[140:141], v[72:73]
	v_mov_b32_e32 v98, v76
	v_pk_fma_f32 v[96:97], v[182:183], v[76:77], v[96:97]
	v_mov_b32_e32 v99, v73
	v_mov_b32_e32 v73, v77
	v_mov_b32_e32 v76, v78
	v_mov_b32_e32 v77, v75
	v_mov_b32_e32 v75, v79
	v_pk_mul_f32 v[76:77], v[76:77], v[124:125]
	v_pk_mul_f32 v[74:75], v[74:75], v[134:135]
	v_pk_mul_f32 v[72:73], v[158:159], v[72:73]
	v_pk_mul_f32 v[76:77], v[76:77], v[94:95] op_sel_hi:[1,0]
	v_pk_mul_f32 v[74:75], v[74:75], v[94:95] op_sel_hi:[1,0]
	v_add3_u32 v88, v202, s69, 48
	v_pk_fma_f32 v[72:73], v[152:153], v[98:99], v[72:73] neg_lo:[0,0,1] neg_hi:[0,0,1]
	v_pk_mul_f32 v[78:79], v[136:137], v[74:75]
	v_mov_b32_e32 v99, v75
	v_mov_b32_e32 v75, v77
	v_ashrrev_i32_e32 v89, 31, v88
	v_mov_b32_e32 v98, v76
	v_pk_mul_f32 v[74:75], v[184:185], v[74:75]
	v_lshlrev_b64 v[88:89], 11, v[88:89]
	v_pk_fma_f32 v[78:79], v[180:181], v[76:77], v[78:79]
	v_pk_fma_f32 v[74:75], v[154:155], v[98:99], v[74:75] neg_lo:[0,0,1] neg_hi:[0,0,1]
	v_lshl_add_u64 v[88:89], v[138:139], 0, v[88:89]
	v_cvt_pk_bf16_f32 v72, v72, v73
	v_cvt_pk_bf16_f32 v73, v74, v75
	v_cvt_pk_bf16_f32 v74, v96, v97
	v_cvt_pk_bf16_f32 v75, v78, v79
	global_store_dwordx4 v[88:89], v[72:75], off sc1
	v_mov_b32_e32 v77, v85
	v_mov_b32_e32 v76, v86
	v_mov_b32_e32 v73, v65
	v_mov_b32_e32 v65, v69
	v_mov_b32_e32 v72, v68
	v_pk_mul_f32 v[64:65], v[64:65], v[128:129]
	v_pk_mul_f32 v[72:73], v[72:73], v[122:123]
	v_pk_mul_f32 v[64:65], v[64:65], v[94:95] op_sel_hi:[1,0]
	v_pk_mul_f32 v[68:69], v[72:73], v[94:95] op_sel_hi:[1,0]
	v_pk_mul_f32 v[72:73], v[64:65], v[86:87]
	v_mov_b32_e32 v75, v65
	v_pk_fma_f32 v[72:73], v[68:69], v[84:85], v[72:73]
	v_mov_b32_e32 v65, v69
	v_mov_b32_e32 v69, v67
	v_mov_b32_e32 v67, v71
	v_mov_b32_e32 v74, v68
	v_mov_b32_e32 v68, v70
	v_pk_mul_f32 v[66:67], v[66:67], v[130:131]
	v_mov_b32_e32 v85, v87
	v_pk_mul_f32 v[68:69], v[68:69], v[126:127]
	v_pk_mul_f32 v[66:67], v[66:67], v[94:95] op_sel_hi:[1,0]
	v_pk_mul_f32 v[64:65], v[64:65], v[84:85]
	v_pk_mul_f32 v[68:69], v[68:69], v[94:95] op_sel_hi:[1,0]
	v_pk_mul_f32 v[70:71], v[66:67], v[82:83]
	v_pk_fma_f32 v[64:65], v[74:75], v[76:77], v[64:65] neg_lo:[0,0,1] neg_hi:[0,0,1]
	v_pk_fma_f32 v[70:71], v[68:69], v[92:93], v[70:71]
	v_mov_b32_e32 v75, v67
	v_mov_b32_e32 v77, v93
	v_mov_b32_e32 v67, v69
	v_mov_b32_e32 v93, v83
	v_mov_b32_e32 v74, v68
	v_mov_b32_e32 v76, v82
	v_pk_mul_f32 v[66:67], v[66:67], v[92:93]
	v_cvt_pk_bf16_f32 v64, v64, v65
	v_pk_fma_f32 v[66:67], v[74:75], v[76:77], v[66:67] neg_lo:[0,0,1] neg_hi:[0,0,1]
	s_and_b64 vcc, exec, s[4:5]
	v_cvt_pk_bf16_f32 v65, v66, v67
	v_cvt_pk_bf16_f32 v66, v72, v73
	v_cvt_pk_bf16_f32 v67, v70, v71
	global_store_dwordx4 v[88:89], v[64:67], off offset:64 sc1
	v_mov_b32_e32 v91, 1.0
	v_mov_b32_e32 v81, 0
	v_mov_b32_e32 v64, 1.0
	v_mov_b32_e32 v76, 0
	v_mov_b32_e32 v77, 1.0
	v_mov_b32_e32 v65, 0
	s_cbranch_vccnz .LBB0_629
	s_lshl_b32 s20, s67, 6
	s_add_i32 s20, s57, s20
	s_ashr_i32 s21, s20, 31
	v_lshl_add_u64 v[64:65], s[20:21], 3, v[178:179]
	global_load_dwordx4 v[80:83], v[64:65], off offset:16
	s_nop 0
	global_load_dwordx4 v[64:67], v[64:65], off
	s_waitcnt vmcnt(1)
	v_mov_b32_e32 v90, v81
	v_mov_b32_e32 v91, v82
	v_mov_b32_e32 v81, v83
	s_waitcnt vmcnt(0)
	v_mov_b32_e32 v76, v65
	v_mov_b32_e32 v77, v66
	v_mov_b32_e32 v65, v67

;     __device__ __forceinline__ void operator()(const f32x4 (&acc)[2][2][4][2], const pg8::Unit& u, int wr, int wc, int fr, int fq) const {
;     ...
;             for (int ai = 0; ai < 2; ++ai) {
;                 const int rpos = 4 * u.pm + 2 * ai + wr;
;                 f32x4 cr0, cr1;
;                 if (kind == 0) { const f32x4* tp = (const f32x4*)(tab + rpos * 16 + 4 * fq); cr0 = tp[0]; cr1 = tp[1]; }
;                 else { cr0 = (f32x4){1.f, 0.f, 1.f, 0.f}; cr1 = cr0; }
; #pragma unroll
;                 for (int m = 0; m < 4; ++m) {
;                     const int t = 256 * u.pm + 128 * ai + 64 * wr + 16 * m + fr;
;                     float ss = 0.f;
; #pragma unroll
;                     for (int bj = 0; bj < 2; ++bj)
; #pragma unroll
;                         for (int n = 0; n < 2; ++n) { const f32x4 v = acc[ai][bj][m][n]; ss += (v[0] * v[0] + v[1] * v[1]) + (v[2] * v[2] + v[3] * v[3]); }
;                     ss += __shfl_xor(ss, 16); ss += __shfl_xor(ss, 32);
;                     const float rstd = __builtin_amdgcn_rsqf(ss * (1.0f / 64.0f) + EPS) * osc;
;                     f32x4 cc0, cc1;
;                     if (kind == 0) { const f32x4* tp = (const f32x4*)(tab + (16 * m + fr) * 16 + 4 * fq); cc0 = tp[0]; cc1 = tp[1]; }
;                     else { cc0 = (f32x4){1.f, 0.f, 1.f, 0.f}; cc1 = cc0; }
;                     bf16_t* rowp = dst + (size_t)(rowoff + t) * 1024 + G * 64 + 8 * fq;
; #pragma unroll
;                     for (int bj = 0; bj < 2; ++bj) {
;                         const f32x4 x1 = acc[ai][bj][m][0] * g[bj][0] * rstd, x2 = acc[ai][bj][m][1] * g[bj][1] * rstd;
;                         const f32x4 ca = bj == 0 ? cr0 : cc0, cb = bj == 0 ? cr1 : cc1;
;                         const float co[4] = {ca[0], ca[2], cb[0], cb[2]}, si[4] = {ca[1], ca[3], cb[1], cb[3]};
;                         float o1[4], o2[4];
; #pragma unroll
;                         for (int e = 0; e < 4; ++e) { o1[e] = x1[e] * co[e] - x2[e] * si[e]; o2[e] = x2[e] * co[e] + x1[e] * si[e]; }
;                         u32x4 w; w.x = cvtpk(o1[0], o1[1]); w.y = cvtpk(o1[2], o1[3]); w.z = cvtpk(o2[0], o2[1]); w.w = cvtpk(o2[2], o2[3]);
;                         *(u32x4*)(rowp + 32 * bj) = w;
;                     }
.LBB0_631:
	s_waitcnt lgkmcnt(0)
	v_add_f32_e32 v67, v67, v79
	v_fmamk_f32 v67, v67, 0x3c800000, v199
	v_rsq_f32_e32 v67, v67
	v_mov_b32_e32 v84, v60
	v_mov_b32_e32 v85, v57
	v_mov_b32_e32 v57, v61
	v_mul_f32_e32 v88, s8, v67
	v_pk_mul_f32 v[84:85], v[84:85], v[142:143]
	v_pk_mul_f32 v[56:57], v[56:57], v[132:133]
	v_pk_mul_f32 v[84:85], v[84:85], v[88:89] op_sel_hi:[1,0]
	v_pk_mul_f32 v[86:87], v[56:57], v[88:89] op_sel_hi:[1,0]
	v_mov_b32_e32 v60, v76
	v_pk_mul_f32 v[56:57], v[64:65], v[86:87]
	v_mov_b32_e32 v95, v87
	v_mov_b32_e32 v61, v65
	v_mov_b32_e32 v87, v85
	v_pk_fma_f32 v[92:93], v[76:77], v[84:85], v[56:57]
	v_mov_b32_e32 v94, v84
	v_pk_mul_f32 v[84:85], v[60:61], v[86:87]
	v_mov_b32_e32 v86, v62
	v_mov_b32_e32 v87, v59
	v_mov_b32_e32 v59, v63
	v_mov_b32_e32 v56, v64
	v_mov_b32_e32 v57, v77
	v_pk_mul_f32 v[86:87], v[86:87], v[124:125]
	v_pk_mul_f32 v[58:59], v[58:59], v[134:135]
	v_pk_fma_f32 v[84:85], v[56:57], v[94:95], v[84:85] neg_lo:[0,0,1] neg_hi:[0,0,1]
	v_pk_mul_f32 v[86:87], v[86:87], v[88:89] op_sel_hi:[1,0]
	v_pk_mul_f32 v[94:95], v[58:59], v[88:89] op_sel_hi:[1,0]
	v_add_u32_e32 v74, 0x80, v146
	v_pk_mul_f32 v[58:59], v[80:81], v[94:95]
	v_mov_b32_e32 v99, v95
	v_mov_b32_e32 v62, v90
	v_mov_b32_e32 v63, v81
	v_mov_b32_e32 v95, v87
	v_ashrrev_i32_e32 v75, 31, v74
	v_pk_fma_f32 v[96:97], v[90:91], v[86:87], v[58:59]
	v_mov_b32_e32 v58, v80
	v_mov_b32_e32 v59, v91
	v_mov_b32_e32 v98, v86
	v_pk_mul_f32 v[86:87], v[62:63], v[94:95]
	v_lshlrev_b64 v[74:75], 11, v[74:75]
	v_pk_fma_f32 v[86:87], v[58:59], v[98:99], v[86:87] neg_lo:[0,0,1] neg_hi:[0,0,1]
	v_lshl_add_u64 v[74:75], v[138:139], 0, v[74:75]
	v_cvt_pk_bf16_f32 v84, v84, v85
	v_cvt_pk_bf16_f32 v85, v86, v87
	v_cvt_pk_bf16_f32 v86, v92, v93
	v_cvt_pk_bf16_f32 v87, v96, v97
	global_store_dwordx4 v[74:75], v[84:87], off sc1
	v_mov_b32_e32 v93, v71
	v_mov_b32_e32 v92, v72
	v_mov_b32_e32 v85, v49
	v_mov_b32_e32 v49, v53
	v_mov_b32_e32 v84, v52
	v_pk_mul_f32 v[48:49], v[48:49], v[128:129]
	v_pk_mul_f32 v[84:85], v[84:85], v[122:123]
	v_pk_mul_f32 v[48:49], v[48:49], v[88:89] op_sel_hi:[1,0]
	v_pk_mul_f32 v[52:53], v[84:85], v[88:89] op_sel_hi:[1,0]
	v_pk_mul_f32 v[84:85], v[48:49], v[72:73]
	v_mov_b32_e32 v87, v49
	v_pk_fma_f32 v[84:85], v[52:53], v[70:71], v[84:85]
	v_mov_b32_e32 v49, v53
	v_mov_b32_e32 v53, v51
	v_mov_b32_e32 v51, v55
	v_mov_b32_e32 v86, v52
	v_mov_b32_e32 v71, v73
	v_mov_b32_e32 v52, v54
	v_pk_mul_f32 v[50:51], v[50:51], v[130:131]
	v_pk_mul_f32 v[48:49], v[48:49], v[70:71]
	v_pk_mul_f32 v[52:53], v[52:53], v[126:127]
	v_pk_mul_f32 v[50:51], v[50:51], v[88:89] op_sel_hi:[1,0]
	v_pk_fma_f32 v[48:49], v[86:87], v[92:93], v[48:49] neg_lo:[0,0,1] neg_hi:[0,0,1]
	v_pk_mul_f32 v[52:53], v[52:53], v[88:89] op_sel_hi:[1,0]
	v_pk_mul_f32 v[54:55], v[50:51], v[68:69]
	v_mov_b32_e32 v70, v52
	v_pk_fma_f32 v[54:55], v[52:53], v[82:83], v[54:55]
	v_cvt_pk_bf16_f32 v48, v48, v49
	v_mul_f32_e32 v49, v45, v45
	v_mul_f32_e32 v52, v47, v47
	v_fmac_f32_e32 v49, v44, v44
	v_fmac_f32_e32 v52, v46, v46
	v_mov_b32_e32 v71, v51
	v_mov_b32_e32 v51, v53
	v_add_f32_e32 v49, v49, v52
	v_mul_f32_e32 v52, v41, v41
	v_mul_f32_e32 v53, v43, v43
	v_fmac_f32_e32 v52, v40, v40
	v_fmac_f32_e32 v53, v42, v42
	v_add_f32_e32 v52, v52, v53
	v_add_f32_e32 v49, v49, v52
	v_mul_f32_e32 v52, v37, v37
	v_mul_f32_e32 v53, v39, v39
	v_fmac_f32_e32 v52, v36, v36
	v_fmac_f32_e32 v53, v38, v38
	v_add_f32_e32 v52, v52, v53
	v_add_f32_e32 v49, v49, v52
	v_mul_f32_e32 v52, v33, v33
	v_mul_f32_e32 v53, v35, v35
	v_fmac_f32_e32 v52, v32, v32
	v_fmac_f32_e32 v53, v34, v34
	v_add_f32_e32 v52, v52, v53
	v_add_f32_e32 v52, v49, v52
	ds_bpermute_b32 v53, v177, v52
	v_mov_b32_e32 v73, v83
	v_mov_b32_e32 v83, v69
	v_mov_b32_e32 v72, v68
	v_pk_mul_f32 v[50:51], v[50:51], v[82:83]
	s_and_b64 vcc, exec, s[4:5]
	v_pk_fma_f32 v[50:51], v[70:71], v[72:73], v[50:51] neg_lo:[0,0,1] neg_hi:[0,0,1]
	v_mov_b32_e32 v79, 1.0
	v_cvt_pk_bf16_f32 v49, v50, v51
	v_cvt_pk_bf16_f32 v51, v54, v55
	s_waitcnt lgkmcnt(0)
	v_add_f32_e32 v54, v52, v53
	ds_bpermute_b32 v55, v201, v54
	v_cvt_pk_bf16_f32 v50, v84, v85
	global_store_dwordx4 v[74:75], v[48:51], off offset:64 sc1
	v_mov_b32_e32 v67, 0
	v_mov_b32_e32 v52, 0
	v_mov_b32_e32 v48, 1.0
	v_mov_b32_e32 v53, 1.0
	v_mov_b32_e32 v49, 0
	s_cbranch_vccnz .LBB0_633
	v_lshlrev_b32_e32 v166, 3, v170
	v_lshl_add_u64 v[48:49], v[178:179], 0, v[166:167]
	global_load_dwordx4 v[66:69], v[48:49], off offset:2064
	s_nop 0
	global_load_dwordx4 v[48:51], v[48:49], off offset:2048
	s_waitcnt vmcnt(1)
	v_mov_b32_e32 v78, v67
	v_mov_b32_e32 v79, v68
	v_mov_b32_e32 v67, v69
	s_waitcnt vmcnt(0)
	v_mov_b32_e32 v52, v49
	v_mov_b32_e32 v53, v50
	v_mov_b32_e32 v49, v51
;     __device__ __forceinline__ void operator()(const f32x4 (&acc)[2][2][4][2], const pg8::Unit& u, int wr, int wc, int fr, int fq) const {
;     ...
;             for (int ai = 0; ai < 2; ++ai) {
;                 const int rpos = 4 * u.pm + 2 * ai + wr;
;                 f32x4 cr0, cr1;
;                 if (kind == 0) { const f32x4* tp = (const f32x4*)(tab + rpos * 16 + 4 * fq); cr0 = tp[0]; cr1 = tp[1]; }
;                 else { cr0 = (f32x4){1.f, 0.f, 1.f, 0.f}; cr1 = cr0; }
; #pragma unroll
;                 for (int m = 0; m < 4; ++m) {
;                     const int t = 256 * u.pm + 128 * ai + 64 * wr + 16 * m + fr;
;                     float ss = 0.f;
; #pragma unroll
;                     for (int bj = 0; bj < 2; ++bj)
; #pragma unroll
;                         for (int n = 0; n < 2; ++n) { const f32x4 v = acc[ai][bj][m][n]; ss += (v[0] * v[0] + v[1] * v[1]) + (v[2] * v[2] + v[3] * v[3]); }
;                     ss += __shfl_xor(ss, 16); ss += __shfl_xor(ss, 32);
;                     const float rstd = __builtin_amdgcn_rsqf(ss * (1.0f / 64.0f) + EPS) * osc;
;                     f32x4 cc0, cc1;
;                     if (kind == 0) { const f32x4* tp = (const f32x4*)(tab + (16 * m + fr) * 16 + 4 * fq); cc0 = tp[0]; cc1 = tp[1]; }
;                     else { cc0 = (f32x4){1.f, 0.f, 1.f, 0.f}; cc1 = cc0; }
;                     bf16_t* rowp = dst + (size_t)(rowoff + t) * 1024 + G * 64 + 8 * fq;
; #pragma unroll
;                     for (int bj = 0; bj < 2; ++bj) {
;                         const f32x4 x1 = acc[ai][bj][m][0] * g[bj][0] * rstd, x2 = acc[ai][bj][m][1] * g[bj][1] * rstd;
;                         const f32x4 ca = bj == 0 ? cr0 : cc0, cb = bj == 0 ? cr1 : cc1;
;                         const float co[4] = {ca[0], ca[2], cb[0], cb[2]}, si[4] = {ca[1], ca[3], cb[1], cb[3]};
;                         float o1[4], o2[4];
; #pragma unroll
;                         for (int e = 0; e < 4; ++e) { o1[e] = x1[e] * co[e] - x2[e] * si[e]; o2[e] = x2[e] * co[e] + x1[e] * si[e]; }
;                         u32x4 w; w.x = cvtpk(o1[0], o1[1]); w.y = cvtpk(o1[2], o1[3]); w.z = cvtpk(o2[0], o2[1]); w.w = cvtpk(o2[2], o2[3]);
;                         *(u32x4*)(rowp + 32 * bj) = w;
;                     }
.LBB0_633:
	s_waitcnt lgkmcnt(0)
	v_add_f32_e32 v50, v54, v55
	v_fmamk_f32 v50, v50, 0x3c800000, v199
	v_rsq_f32_e32 v54, v50
	v_mov_b32_e32 v69, v41
	v_mov_b32_e32 v41, v45
	v_mov_b32_e32 v68, v44
	v_mul_f32_e32 v54, s8, v54
	v_pk_mul_f32 v[40:41], v[40:41], v[132:133]
	v_pk_mul_f32 v[68:69], v[68:69], v[142:143]
	v_pk_mul_f32 v[40:41], v[40:41], v[54:55] op_sel_hi:[1,0]
	v_pk_mul_f32 v[44:45], v[68:69], v[54:55] op_sel_hi:[1,0]
	v_pk_mul_f32 v[68:69], v[64:65], v[40:41]
	v_mov_b32_e32 v70, v44
	v_pk_fma_f32 v[68:69], v[76:77], v[44:45], v[68:69]
	v_mov_b32_e32 v71, v41
	v_mov_b32_e32 v41, v45
	v_mov_b32_e32 v44, v46
	v_mov_b32_e32 v45, v43
	v_mov_b32_e32 v43, v47
	v_pk_mul_f32 v[44:45], v[44:45], v[124:125]
	v_pk_mul_f32 v[42:43], v[42:43], v[134:135]
	v_pk_mul_f32 v[40:41], v[60:61], v[40:41]
	v_pk_mul_f32 v[44:45], v[44:45], v[54:55] op_sel_hi:[1,0]
	v_pk_mul_f32 v[42:43], v[42:43], v[54:55] op_sel_hi:[1,0]
	v_add_u32_e32 v50, 0x90, v146
	v_pk_fma_f32 v[40:41], v[56:57], v[70:71], v[40:41] neg_lo:[0,0,1] neg_hi:[0,0,1]
	v_pk_mul_f32 v[46:47], v[80:81], v[42:43]
	v_mov_b32_e32 v71, v43
	v_mov_b32_e32 v43, v45
	v_ashrrev_i32_e32 v51, 31, v50
	v_mov_b32_e32 v70, v44
	v_pk_mul_f32 v[42:43], v[62:63], v[42:43]
	v_lshlrev_b64 v[50:51], 11, v[50:51]
	v_pk_fma_f32 v[46:47], v[90:91], v[44:45], v[46:47]
	v_pk_fma_f32 v[42:43], v[58:59], v[70:71], v[42:43] neg_lo:[0,0,1] neg_hi:[0,0,1]
	v_lshl_add_u64 v[50:51], v[138:139], 0, v[50:51]
	v_cvt_pk_bf16_f32 v40, v40, v41
	v_cvt_pk_bf16_f32 v41, v42, v43
	v_cvt_pk_bf16_f32 v42, v68, v69
	v_cvt_pk_bf16_f32 v43, v46, v47
	global_store_dwordx4 v[50:51], v[40:43], off sc1
	v_mov_b32_e32 v45, v53
	v_mov_b32_e32 v44, v48
	v_mov_b32_e32 v41, v33
	v_mov_b32_e32 v33, v37
	v_mov_b32_e32 v40, v36
	v_pk_mul_f32 v[32:33], v[32:33], v[128:129]
	v_pk_mul_f32 v[40:41], v[40:41], v[122:123]
	v_pk_mul_f32 v[32:33], v[32:33], v[54:55] op_sel_hi:[1,0]
	v_pk_mul_f32 v[36:37], v[40:41], v[54:55] op_sel_hi:[1,0]
	v_pk_mul_f32 v[40:41], v[32:33], v[48:49]
	v_mov_b32_e32 v43, v33
	v_pk_fma_f32 v[40:41], v[36:37], v[52:53], v[40:41]
	v_mov_b32_e32 v33, v37
	v_mov_b32_e32 v37, v35
	v_mov_b32_e32 v35, v39
	v_mov_b32_e32 v42, v36
	v_mov_b32_e32 v53, v49
	v_mov_b32_e32 v36, v38
	v_pk_mul_f32 v[34:35], v[34:35], v[130:131]
	v_pk_mul_f32 v[32:33], v[32:33], v[52:53]
	v_pk_mul_f32 v[36:37], v[36:37], v[126:127]
	v_pk_mul_f32 v[34:35], v[34:35], v[54:55] op_sel_hi:[1,0]
	v_pk_fma_f32 v[32:33], v[42:43], v[44:45], v[32:33] neg_lo:[0,0,1] neg_hi:[0,0,1]
	v_pk_mul_f32 v[36:37], v[36:37], v[54:55] op_sel_hi:[1,0]
	v_pk_mul_f32 v[38:39], v[34:35], v[66:67]
	v_mov_b32_e32 v42, v36
	v_pk_fma_f32 v[38:39], v[36:37], v[78:79], v[38:39]
	v_cvt_pk_bf16_f32 v32, v32, v33
	v_mul_f32_e32 v33, v29, v29
	v_mul_f32_e32 v36, v31, v31
	v_fmac_f32_e32 v33, v28, v28
	v_fmac_f32_e32 v36, v30, v30
	v_mov_b32_e32 v43, v35
	v_mov_b32_e32 v35, v37
	v_add_f32_e32 v33, v33, v36
	v_mul_f32_e32 v36, v25, v25
	v_mul_f32_e32 v37, v27, v27
	v_fmac_f32_e32 v36, v24, v24
	v_fmac_f32_e32 v37, v26, v26
	v_add_f32_e32 v36, v36, v37
	v_add_f32_e32 v33, v33, v36
	v_mul_f32_e32 v36, v21, v21
	v_mul_f32_e32 v37, v23, v23
	v_fmac_f32_e32 v36, v20, v20
	v_fmac_f32_e32 v37, v22, v22
	v_add_f32_e32 v36, v36, v37
	v_add_f32_e32 v33, v33, v36
	v_mul_f32_e32 v36, v17, v17
	v_mul_f32_e32 v37, v19, v19
	v_fmac_f32_e32 v36, v16, v16
	v_fmac_f32_e32 v37, v18, v18
	v_add_f32_e32 v36, v36, v37
	v_add_f32_e32 v36, v33, v36
	ds_bpermute_b32 v37, v177, v36
	v_mov_b32_e32 v45, v79
	v_mov_b32_e32 v79, v67
	v_mov_b32_e32 v44, v66
	v_pk_mul_f32 v[34:35], v[34:35], v[78:79]
	s_and_b64 vcc, exec, s[4:5]
	v_pk_fma_f32 v[34:35], v[42:43], v[44:45], v[34:35] neg_lo:[0,0,1] neg_hi:[0,0,1]
	v_mov_b32_e32 v42, 0
	v_cvt_pk_bf16_f32 v33, v34, v35
	v_cvt_pk_bf16_f32 v34, v40, v41
	v_cvt_pk_bf16_f32 v35, v38, v39
	global_store_dwordx4 v[50:51], v[32:35], off offset:64 sc1
	v_mov_b32_e32 v44, 0
	v_mov_b32_e32 v45, 1.0
	s_waitcnt lgkmcnt(0)
	v_add_f32_e32 v33, v36, v37
	ds_bpermute_b32 v43, v201, v33
	v_mov_b32_e32 v32, 1.0
	v_mov_b32_e32 v34, 1.0
	v_mov_b32_e32 v35, 0
	v_mov_b32_e32 v38, 1.0
	v_mov_b32_e32 v36, 0
	v_mov_b32_e32 v37, 1.0
	v_mov_b32_e32 v39, 0
	s_cbranch_vccnz .LBB0_635
	v_lshlrev_b32_e32 v166, 3, v170
	v_lshl_add_u64 v[38:39], v[178:179], 0, v[166:167]
	v_lshl_add_u64 v[34:35], v[38:39], 0, s[34:35]
	v_add_co_u32_e32 v38, vcc, 0x1000, v38
	global_load_dwordx4 v[34:37], v[34:35], off offset:16
	s_nop 0
	v_addc_co_u32_e32 v39, vcc, 0, v39, vcc
	global_load_dwordx4 v[38:41], v[38:39], off
	s_waitcnt vmcnt(1)
	v_mov_b32_e32 v44, v35
	v_mov_b32_e32 v45, v36
	v_mov_b32_e32 v35, v37
	s_waitcnt vmcnt(0)
	v_mov_b32_e32 v36, v39
	v_mov_b32_e32 v37, v40
	v_mov_b32_e32 v39, v41
;     __device__ __forceinline__ void operator()(const f32x4 (&acc)[2][2][4][2], const pg8::Unit& u, int wr, int wc, int fr, int fq) const {
;     ...
;             for (int ai = 0; ai < 2; ++ai) {
;                 const int rpos = 4 * u.pm + 2 * ai + wr;
;                 f32x4 cr0, cr1;
;                 if (kind == 0) { const f32x4* tp = (const f32x4*)(tab + rpos * 16 + 4 * fq); cr0 = tp[0]; cr1 = tp[1]; }
;                 else { cr0 = (f32x4){1.f, 0.f, 1.f, 0.f}; cr1 = cr0; }
; #pragma unroll
;                 for (int m = 0; m < 4; ++m) {
;                     const int t = 256 * u.pm + 128 * ai + 64 * wr + 16 * m + fr;
;                     float ss = 0.f;
; #pragma unroll
;                     for (int bj = 0; bj < 2; ++bj)
; #pragma unroll
;                         for (int n = 0; n < 2; ++n) { const f32x4 v = acc[ai][bj][m][n]; ss += (v[0] * v[0] + v[1] * v[1]) + (v[2] * v[2] + v[3] * v[3]); }
;                     ss += __shfl_xor(ss, 16); ss += __shfl_xor(ss, 32);
;                     const float rstd = __builtin_amdgcn_rsqf(ss * (1.0f / 64.0f) + EPS) * osc;
;                     f32x4 cc0, cc1;
;                     if (kind == 0) { const f32x4* tp = (const f32x4*)(tab + (16 * m + fr) * 16 + 4 * fq); cc0 = tp[0]; cc1 = tp[1]; }
;                     else { cc0 = (f32x4){1.f, 0.f, 1.f, 0.f}; cc1 = cc0; }
;                     bf16_t* rowp = dst + (size_t)(rowoff + t) * 1024 + G * 64 + 8 * fq;
; #pragma unroll
;                     for (int bj = 0; bj < 2; ++bj) {
;                         const f32x4 x1 = acc[ai][bj][m][0] * g[bj][0] * rstd, x2 = acc[ai][bj][m][1] * g[bj][1] * rstd;
;                         const f32x4 ca = bj == 0 ? cr0 : cc0, cb = bj == 0 ? cr1 : cc1;
;                         const float co[4] = {ca[0], ca[2], cb[0], cb[2]}, si[4] = {ca[1], ca[3], cb[1], cb[3]};
;                         float o1[4], o2[4];
; #pragma unroll
;                         for (int e = 0; e < 4; ++e) { o1[e] = x1[e] * co[e] - x2[e] * si[e]; o2[e] = x2[e] * co[e] + x1[e] * si[e]; }
;                         u32x4 w; w.x = cvtpk(o1[0], o1[1]); w.y = cvtpk(o1[2], o1[3]); w.z = cvtpk(o2[0], o2[1]); w.w = cvtpk(o2[2], o2[3]);
;                         *(u32x4*)(rowp + 32 * bj) = w;
;                     }
.LBB0_635:
	s_waitcnt lgkmcnt(0)
	v_add_f32_e32 v33, v33, v43
	v_fmamk_f32 v33, v33, 0x3c800000, v199
	v_rsq_f32_e32 v33, v33
	v_mov_b32_e32 v49, v25
	v_mov_b32_e32 v25, v29
	v_mov_b32_e32 v48, v28
	v_mul_f32_e32 v46, s8, v33
	v_pk_mul_f32 v[24:25], v[24:25], v[132:133]
	v_pk_mul_f32 v[48:49], v[48:49], v[142:143]
	v_pk_mul_f32 v[24:25], v[24:25], v[46:47] op_sel_hi:[1,0]
	v_pk_mul_f32 v[28:29], v[48:49], v[46:47] op_sel_hi:[1,0]
	v_pk_mul_f32 v[48:49], v[64:65], v[24:25]
	v_mov_b32_e32 v50, v28
	v_pk_fma_f32 v[48:49], v[76:77], v[28:29], v[48:49]
	v_mov_b32_e32 v51, v25
	v_mov_b32_e32 v25, v29
	v_mov_b32_e32 v28, v30
	v_mov_b32_e32 v29, v27
	v_mov_b32_e32 v27, v31
	v_pk_mul_f32 v[28:29], v[28:29], v[124:125]
	v_pk_mul_f32 v[26:27], v[26:27], v[134:135]
	v_pk_mul_f32 v[24:25], v[60:61], v[24:25]
	v_pk_mul_f32 v[28:29], v[28:29], v[46:47] op_sel_hi:[1,0]
	v_pk_mul_f32 v[26:27], v[26:27], v[46:47] op_sel_hi:[1,0]
	v_add_u32_e32 v40, 0xa0, v146
	v_pk_fma_f32 v[24:25], v[56:57], v[50:51], v[24:25] neg_lo:[0,0,1] neg_hi:[0,0,1]
	v_pk_mul_f32 v[30:31], v[80:81], v[26:27]
	v_mov_b32_e32 v51, v27
	v_mov_b32_e32 v27, v29
	v_ashrrev_i32_e32 v41, 31, v40
	v_mov_b32_e32 v50, v28
	v_pk_mul_f32 v[26:27], v[62:63], v[26:27]
	v_lshlrev_b64 v[40:41], 11, v[40:41]
	v_pk_fma_f32 v[30:31], v[90:91], v[28:29], v[30:31]
	v_pk_fma_f32 v[26:27], v[58:59], v[50:51], v[26:27] neg_lo:[0,0,1] neg_hi:[0,0,1]
	v_lshl_add_u64 v[40:41], v[138:139], 0, v[40:41]
	v_cvt_pk_bf16_f32 v24, v24, v25
	v_cvt_pk_bf16_f32 v25, v26, v27
	v_cvt_pk_bf16_f32 v26, v48, v49
	v_cvt_pk_bf16_f32 v27, v30, v31
	global_store_dwordx4 v[40:41], v[24:27], off sc1
	v_mov_b32_e32 v29, v37
	v_mov_b32_e32 v28, v38
	v_mov_b32_e32 v25, v17
	v_mov_b32_e32 v17, v21
	v_mov_b32_e32 v24, v20
	v_pk_mul_f32 v[16:17], v[16:17], v[128:129]
	v_pk_mul_f32 v[24:25], v[24:25], v[122:123]
	v_pk_mul_f32 v[16:17], v[16:17], v[46:47] op_sel_hi:[1,0]
	v_pk_mul_f32 v[20:21], v[24:25], v[46:47] op_sel_hi:[1,0]
	v_pk_mul_f32 v[24:25], v[16:17], v[38:39]
	v_mov_b32_e32 v27, v17
	v_pk_fma_f32 v[24:25], v[20:21], v[36:37], v[24:25]
	v_mov_b32_e32 v17, v21
	v_mov_b32_e32 v21, v19
	v_mov_b32_e32 v19, v23
	v_mov_b32_e32 v26, v20
	v_mov_b32_e32 v37, v39
	v_mov_b32_e32 v20, v22
	v_pk_mul_f32 v[18:19], v[18:19], v[130:131]
	v_pk_mul_f32 v[16:17], v[16:17], v[36:37]
	v_pk_mul_f32 v[20:21], v[20:21], v[126:127]
	v_pk_mul_f32 v[18:19], v[18:19], v[46:47] op_sel_hi:[1,0]
	v_pk_fma_f32 v[16:17], v[26:27], v[28:29], v[16:17] neg_lo:[0,0,1] neg_hi:[0,0,1]
	v_pk_mul_f32 v[20:21], v[20:21], v[46:47] op_sel_hi:[1,0]
	v_pk_mul_f32 v[22:23], v[18:19], v[34:35]
	v_mov_b32_e32 v26, v20
	v_pk_fma_f32 v[22:23], v[20:21], v[44:45], v[22:23]
	v_cvt_pk_bf16_f32 v16, v16, v17
	v_mul_f32_e32 v17, v13, v13
	v_mul_f32_e32 v20, v15, v15
	v_fmac_f32_e32 v17, v12, v12
	v_fmac_f32_e32 v20, v14, v14
	v_mov_b32_e32 v27, v19
	v_mov_b32_e32 v19, v21
	v_add_f32_e32 v17, v17, v20
	v_mul_f32_e32 v20, v9, v9
	v_mul_f32_e32 v21, v11, v11
	v_fmac_f32_e32 v20, v8, v8
	v_fmac_f32_e32 v21, v10, v10
	v_add_f32_e32 v20, v20, v21
	v_add_f32_e32 v17, v17, v20
	v_mul_f32_e32 v20, v5, v5
	v_mul_f32_e32 v21, v7, v7
	v_fmac_f32_e32 v20, v4, v4
	v_fmac_f32_e32 v21, v6, v6
	v_add_f32_e32 v20, v20, v21
	v_add_f32_e32 v17, v17, v20
	v_mul_f32_e32 v20, v1, v1
	v_mul_f32_e32 v21, v3, v3
	v_fmac_f32_e32 v20, v0, v0
	v_fmac_f32_e32 v21, v2, v2
	v_add_f32_e32 v20, v20, v21
	v_add_f32_e32 v20, v17, v20
	ds_bpermute_b32 v21, v177, v20
	v_mov_b32_e32 v29, v45
	v_mov_b32_e32 v45, v35
	v_mov_b32_e32 v28, v34
	v_pk_mul_f32 v[18:19], v[18:19], v[44:45]
	s_and_b64 vcc, exec, s[4:5]
	v_pk_fma_f32 v[18:19], v[26:27], v[28:29], v[18:19] neg_lo:[0,0,1] neg_hi:[0,0,1]
	v_mov_b32_e32 v43, 1.0
	v_cvt_pk_bf16_f32 v17, v18, v19
	v_cvt_pk_bf16_f32 v19, v22, v23
	s_waitcnt lgkmcnt(0)
	v_add_f32_e32 v22, v20, v21
	ds_bpermute_b32 v23, v201, v22
	v_cvt_pk_bf16_f32 v18, v24, v25
	global_store_dwordx4 v[40:41], v[16:19], off offset:64 sc1
	v_mov_b32_e32 v33, 0
	v_mov_b32_e32 v20, 0
	v_mov_b32_e32 v16, 1.0
	v_mov_b32_e32 v21, 1.0
	v_mov_b32_e32 v17, 0
	s_cbranch_vccnz .LBB0_637
	v_lshlrev_b32_e32 v166, 3, v170
	v_lshl_add_u64 v[16:17], v[178:179], 0, v[166:167]
	v_lshl_add_u64 v[18:19], v[16:17], 0, s[36:37]
	v_add_co_u32_e32 v16, vcc, 0x1000, v16
	global_load_dwordx4 v[32:35], v[18:19], off offset:16
	s_nop 0
	v_addc_co_u32_e32 v17, vcc, 0, v17, vcc
	global_load_dwordx4 v[16:19], v[16:17], off offset:2048
	s_waitcnt vmcnt(1)
	v_mov_b32_e32 v42, v33
	v_mov_b32_e32 v43, v34
	v_mov_b32_e32 v33, v35
	s_waitcnt vmcnt(0)
	v_mov_b32_e32 v20, v17
	v_mov_b32_e32 v21, v18
	v_mov_b32_e32 v17, v19
;     __device__ __forceinline__ void operator()(const f32x4 (&acc)[2][2][4][2], const pg8::Unit& u, int wr, int wc, int fr, int fq) const {
;     ...
;             for (int ai = 0; ai < 2; ++ai) {
;                 const int rpos = 4 * u.pm + 2 * ai + wr;
;                 f32x4 cr0, cr1;
;                 if (kind == 0) { const f32x4* tp = (const f32x4*)(tab + rpos * 16 + 4 * fq); cr0 = tp[0]; cr1 = tp[1]; }
;                 else { cr0 = (f32x4){1.f, 0.f, 1.f, 0.f}; cr1 = cr0; }
; #pragma unroll
;                 for (int m = 0; m < 4; ++m) {
;                     const int t = 256 * u.pm + 128 * ai + 64 * wr + 16 * m + fr;
;                     float ss = 0.f;
; #pragma unroll
;                     for (int bj = 0; bj < 2; ++bj)
; #pragma unroll
;                         for (int n = 0; n < 2; ++n) { const f32x4 v = acc[ai][bj][m][n]; ss += (v[0] * v[0] + v[1] * v[1]) + (v[2] * v[2] + v[3] * v[3]); }
;                     ss += __shfl_xor(ss, 16); ss += __shfl_xor(ss, 32);
;                     const float rstd = __builtin_amdgcn_rsqf(ss * (1.0f / 64.0f) + EPS) * osc;
;                     f32x4 cc0, cc1;
;                     if (kind == 0) { const f32x4* tp = (const f32x4*)(tab + (16 * m + fr) * 16 + 4 * fq); cc0 = tp[0]; cc1 = tp[1]; }
;                     else { cc0 = (f32x4){1.f, 0.f, 1.f, 0.f}; cc1 = cc0; }
;                     bf16_t* rowp = dst + (size_t)(rowoff + t) * 1024 + G * 64 + 8 * fq;
; #pragma unroll
;                     for (int bj = 0; bj < 2; ++bj) {
;                         const f32x4 x1 = acc[ai][bj][m][0] * g[bj][0] * rstd, x2 = acc[ai][bj][m][1] * g[bj][1] * rstd;
;                         const f32x4 ca = bj == 0 ? cr0 : cc0, cb = bj == 0 ? cr1 : cc1;
;                         const float co[4] = {ca[0], ca[2], cb[0], cb[2]}, si[4] = {ca[1], ca[3], cb[1], cb[3]};
;                         float o1[4], o2[4];
; #pragma unroll
;                         for (int e = 0; e < 4; ++e) { o1[e] = x1[e] * co[e] - x2[e] * si[e]; o2[e] = x2[e] * co[e] + x1[e] * si[e]; }
;                         u32x4 w; w.x = cvtpk(o1[0], o1[1]); w.y = cvtpk(o1[2], o1[3]); w.z = cvtpk(o2[0], o2[1]); w.w = cvtpk(o2[2], o2[3]);
;                         *(u32x4*)(rowp + 32 * bj) = w;
;                     }
.LBB0_637:
	s_waitcnt lgkmcnt(0)
	v_add_f32_e32 v18, v22, v23
	v_fmamk_f32 v18, v18, 0x3c800000, v199
	v_rsq_f32_e32 v22, v18
	v_mov_b32_e32 v25, v9
	v_mov_b32_e32 v9, v13
	v_mov_b32_e32 v24, v12
	v_mul_f32_e32 v22, s8, v22
	v_pk_mul_f32 v[8:9], v[8:9], v[132:133]
	v_pk_mul_f32 v[24:25], v[24:25], v[142:143]
	v_pk_mul_f32 v[8:9], v[8:9], v[22:23] op_sel_hi:[1,0]
	v_pk_mul_f32 v[12:13], v[24:25], v[22:23] op_sel_hi:[1,0]
	v_pk_mul_f32 v[24:25], v[64:65], v[8:9]
	v_mov_b32_e32 v26, v12
	v_pk_fma_f32 v[24:25], v[76:77], v[12:13], v[24:25]
	v_mov_b32_e32 v27, v9
	v_mov_b32_e32 v9, v13
	v_mov_b32_e32 v12, v14
	v_mov_b32_e32 v13, v11
	v_mov_b32_e32 v11, v15
	v_pk_mul_f32 v[12:13], v[12:13], v[124:125]
	v_pk_mul_f32 v[10:11], v[10:11], v[134:135]
	v_pk_mul_f32 v[8:9], v[60:61], v[8:9]
	v_pk_mul_f32 v[12:13], v[12:13], v[22:23] op_sel_hi:[1,0]
	v_pk_mul_f32 v[10:11], v[10:11], v[22:23] op_sel_hi:[1,0]
	v_add_u32_e32 v18, 0xb0, v146
	v_pk_fma_f32 v[8:9], v[56:57], v[26:27], v[8:9] neg_lo:[0,0,1] neg_hi:[0,0,1]
	v_pk_mul_f32 v[14:15], v[80:81], v[10:11]
	v_mov_b32_e32 v27, v11
	v_mov_b32_e32 v11, v13
	v_ashrrev_i32_e32 v19, 31, v18
	v_mov_b32_e32 v26, v12
	v_pk_mul_f32 v[10:11], v[62:63], v[10:11]
	v_lshlrev_b64 v[18:19], 11, v[18:19]
	v_pk_fma_f32 v[14:15], v[90:91], v[12:13], v[14:15]
	v_pk_fma_f32 v[10:11], v[58:59], v[26:27], v[10:11] neg_lo:[0,0,1] neg_hi:[0,0,1]
	v_lshl_add_u64 v[18:19], v[138:139], 0, v[18:19]
	v_cvt_pk_bf16_f32 v8, v8, v9
	v_cvt_pk_bf16_f32 v9, v10, v11
	v_cvt_pk_bf16_f32 v10, v24, v25
	v_cvt_pk_bf16_f32 v11, v14, v15
	global_store_dwordx4 v[18:19], v[8:11], off sc1
	v_mov_b32_e32 v13, v21
	v_mov_b32_e32 v12, v16
	v_mov_b32_e32 v9, v1
	v_mov_b32_e32 v1, v5
	v_mov_b32_e32 v8, v4
	v_pk_mul_f32 v[0:1], v[0:1], v[128:129]
	v_pk_mul_f32 v[8:9], v[8:9], v[122:123]
	v_pk_mul_f32 v[0:1], v[0:1], v[22:23] op_sel_hi:[1,0]
	v_pk_mul_f32 v[4:5], v[8:9], v[22:23] op_sel_hi:[1,0]
	v_pk_mul_f32 v[8:9], v[0:1], v[16:17]
	v_mov_b32_e32 v11, v1
	v_pk_fma_f32 v[8:9], v[4:5], v[20:21], v[8:9]
	v_mov_b32_e32 v1, v5
	v_mov_b32_e32 v5, v3
	v_mov_b32_e32 v3, v7
	v_mov_b32_e32 v10, v4
	v_mov_b32_e32 v4, v6
	v_pk_mul_f32 v[2:3], v[2:3], v[130:131]
	v_mov_b32_e32 v21, v17
	v_pk_mul_f32 v[4:5], v[4:5], v[126:127]
	v_pk_mul_f32 v[2:3], v[2:3], v[22:23] op_sel_hi:[1,0]
	v_pk_mul_f32 v[0:1], v[0:1], v[20:21]
	v_pk_mul_f32 v[4:5], v[4:5], v[22:23] op_sel_hi:[1,0]
	v_pk_mul_f32 v[6:7], v[2:3], v[32:33]
	v_pk_fma_f32 v[0:1], v[10:11], v[12:13], v[0:1] neg_lo:[0,0,1] neg_hi:[0,0,1]
	v_pk_fma_f32 v[6:7], v[4:5], v[42:43], v[6:7]
	v_mov_b32_e32 v11, v3
	v_mov_b32_e32 v13, v43
	v_mov_b32_e32 v3, v5
	v_mov_b32_e32 v43, v33
	v_mov_b32_e32 v10, v4
	v_mov_b32_e32 v12, v32
	v_pk_mul_f32 v[2:3], v[2:3], v[42:43]
	v_cvt_pk_bf16_f32 v0, v0, v1
	v_pk_fma_f32 v[2:3], v[10:11], v[12:13], v[2:3] neg_lo:[0,0,1] neg_hi:[0,0,1]
	s_nop 0
	v_cvt_pk_bf16_f32 v1, v2, v3
	v_cvt_pk_bf16_f32 v2, v8, v9
	v_cvt_pk_bf16_f32 v3, v6, v7
	global_store_dwordx4 v[18:19], v[0:3], off offset:64 sc1
	s_andn2_b64 vcc, exec, s[38:39]
	s_mov_b64 s[4:5], -1
	s_cbranch_vccnz .LBB0_582

; __device__ __forceinline__ unsigned xb_ld(unsigned* p)              { return __hip_atomic_load(p, __ATOMIC_RELAXED, __HIP_MEMORY_SCOPE_AGENT); }
; __device__ __forceinline__ unsigned xb_add(unsigned* p, unsigned v) { return __hip_atomic_fetch_add(p, v, __ATOMIC_RELAXED, __HIP_MEMORY_SCOPE_AGENT); }
; #define XB_SPIN(cond, bar) do { unsigned _sp = 0; while (cond) { __builtin_amdgcn_s_sleep(1); \
;     if ((++_sp & 255u) == 0u) { if (xb_ld(&(bar)[XB_TMO])) break; if (_sp > XB_SPIN_CAP) { atomicAdd(&(bar)[XB_TMO], 1u); break; } } } } while (0)
; #define BOTH(k) (IN(k) && IN((k) + 1))
; #define GRID_SYNC() xcd_barrier(gbar)
; __device__ __forceinline__ void xcd_barrier(const XcdBarrier& b) {
;     asm volatile("s_waitcnt vmcnt(0)" ::: "memory");
;     __syncthreads();
;     if (threadIdx.x == 0) {
;         unsigned* bar = b.bar;
;         __builtin_amdgcn_s_waitcnt(0);
;         unsigned nloc = b.st[0], nx = b.st[1];
;         if (nloc == 0u) { unsigned uni; xcd_barrier_complete(bar, b.x, nloc, nx, uni); b.st[0] = nloc; b.st[1] = nx; b.st[2] = uni; }
;         const unsigned old = xb_add(&bar[XB_XSUB(b.x)], 1u);
;         const unsigned gen = old / nloc;
;         if (old + 1u == (gen + 1u) * nloc) {
;             __builtin_amdgcn_fence(__ATOMIC_RELEASE, "agent");
;             asm volatile("s_waitcnt vmcnt(0)" ::: "memory");
;             const unsigned og = xb_add(&bar[XB_TOP], 1u);
;             const unsigned tg = og / nx;
;             if (og + 1u == (tg + 1u) * nx) xb_add(&bar[XB_TOPGEN], 1u);
;             else XB_SPIN(xb_ld(&bar[XB_TOPGEN]) == tg, bar);
;             __builtin_amdgcn_fence(__ATOMIC_ACQUIRE, "agent");
;             xb_add(&bar[XB_XGEN(b.x)], 1u);
;             asm volatile("s_waitcnt vmcnt(0)" ::: "memory");
;         } else {
;             XB_SPIN(xb_ld(&bar[XB_XGEN(b.x)]) == gen, bar);
;             __builtin_amdgcn_fence(__ATOMIC_ACQUIRE, "agent");
;             asm volatile("s_waitcnt vmcnt(0)" ::: "memory");
;         }
;     }
;     __syncthreads();
; }
; __global__ void __launch_bounds__(512, 2) fwd_kernel(Args args) {
;     ...
;         if (BOTH(2)) GRID_SYNC();
.LBB0_642:
	s_waitcnt lgkmcnt(0)
	s_cmp_lt_i32 s35, 4
	s_cbranch_scc1 .LBB0_697
	s_waitcnt vmcnt(0)
	s_barrier
	s_mov_b64 s[20:21], exec
	v_readlane_b32 s4, v246, 3
	v_readlane_b32 s5, v246, 4
	s_and_b64 s[4:5], s[20:21], s[4:5]
	s_mov_b64 exec, s[4:5]
	s_cbranch_execz .Lb3_join
	s_add_u32 s4, s26, 0xfa00
	s_addc_u32 s5, s27, 0
	s_add_u32 s6, s26, 0xf500
	s_addc_u32 s7, s27, 0
	v_mov_b32_e32 v0, 0
	s_mov_b32 s3, 0
	s_cmpk_gt_i32 s2, 0x87
	s_cbranch_scc1 .Lb3_spin
	v_mov_b32_e32 v1, 1
	global_atomic_add v0, v1, s[4:5]
	s_waitcnt vmcnt(0)
.Lb3_spin:
	global_load_dword v1, v0, s[4:5] sc1
	global_load_dword v2, v0, s[6:7] sc1
	s_waitcnt vmcnt(0)
	v_cmp_eq_u32_e32 vcc, 0x88, v1
	v_cmp_lt_u32_e64 s[8:9], 1, v2
	s_and_b64 s[8:9], vcc, s[8:9]
	s_and_b64 s[8:9], s[8:9], exec
	s_cbranch_scc1 .Lb3_done
	s_sleep 1
	s_add_i32 s3, s3, 1
	s_cmp_lt_u32 s3, 0x100000
	s_cbranch_scc1 .Lb3_spin
.Lb3_done:
	buffer_inv sc1
	s_waitcnt vmcnt(0)
.Lb3_join:
	s_or_b64 exec, exec, s[20:21]
	s_waitcnt lgkmcnt(0)
	s_barrier
	s_branch .LBB0_697
	s_waitcnt vmcnt(0)
	s_waitcnt vmcnt(0)
	s_barrier
	s_mov_b64 s[20:21], exec
	v_readlane_b32 s4, v246, 3
	v_readlane_b32 s5, v246, 4
	s_and_b64 s[4:5], s[20:21], s[4:5]
	s_mov_b64 exec, s[4:5]
	s_cbranch_execz .LBB0_696
	s_add_i32 s3, 0, 0x23fc0
	v_mov_b32_e32 v0, s3
	s_waitcnt vmcnt(0) expcnt(0) lgkmcnt(0)
	ds_read_b32 v2, v0
	s_add_i32 s3, 0, 0x23fc4
	v_mov_b32_e32 v0, s3
	ds_read_b32 v0, v0
	s_waitcnt lgkmcnt(1)
	v_cmp_ne_u32_e32 vcc, 0, v2
	s_cbranch_vccnz .LBB0_658
	s_add_u32 s4, s26, 0xc200
	s_addc_u32 s5, s27, 0
	s_add_u32 s6, s26, 0xc400
	s_addc_u32 s7, s27, 0
	s_add_u32 s8, s26, 0xc500
	s_addc_u32 s9, s27, 0
	s_add_u32 s10, s26, 0xc600
	s_addc_u32 s11, s27, 0
	s_add_u32 s12, s26, 0xc700
	s_addc_u32 s13, s27, 0
	s_add_u32 s14, s26, 0xc800
	s_addc_u32 s15, s27, 0
	s_add_u32 s16, s26, 0xc900
	s_addc_u32 s17, s27, 0
	s_add_u32 s18, s26, 0xca00
	s_addc_u32 s19, s27, 0
	s_add_u32 s30, s26, 0xcb00
	s_addc_u32 s31, s27, 0
	s_add_u32 s34, s26, 0xcc00
	s_addc_u32 s35, s27, 0
	s_add_u32 s36, s26, 0xcd00
	s_addc_u32 s37, s27, 0
	s_add_u32 s38, s26, 0xce00
	s_addc_u32 s39, s27, 0
	s_add_u32 s40, s26, 0xcf00
	s_addc_u32 s41, s27, 0
	s_add_u32 s42, s26, 0xd000
	s_load_dword s3, s[0:1], 0xc0
	s_addc_u32 s43, s27, 0
	s_add_u32 s44, s26, 0xd100
	s_addc_u32 s45, s27, 0
	s_add_u32 s46, s26, 0xd200
	s_addc_u32 s47, s27, 0
	s_waitcnt lgkmcnt(0)
	s_mul_i32 s3, s23, s3
	s_add_u32 s48, s26, 0xd300
	s_mul_i32 s3, s3, s22
	s_addc_u32 s49, s27, 0
	s_mov_b32 s24, 1
	v_mov_b32_e32 v16, 0
	s_branch .LBB0_647
